# attention: split-halves passes software-pipelined (PV of previous half tile under exp/pack of current), 3x slot-unrolled; P2 SSM scan hand-written with prefetch; P5 epilogue
# speedup vs baseline: 1.0836x; 1.0250x over previous
.LBB0_203:
	s_bfe_u32 s31, s3, 0x50006
	s_lshl_b32 s30, s31, 6
	v_or_b32_e32 v0, s30, v160
	v_lshlrev_b32_e32 v0, 2, v0
	global_load_dword v86, v0, s[12:13]
	global_load_dword v88, v0, s[14:15]
	v_lshl_or_b32 v0, s31, 12, v162
	global_load_dwordx4 v[64:67], v0, s[18:19] offset:1024
	global_load_dwordx4 v[68:71], v0, s[18:19] offset:2048
	global_load_dwordx4 v[72:75], v0, s[18:19] offset:3072
	global_load_dwordx4 v[76:79], v0, s[18:19]
	s_lshl_b32 s34, s31, 5
	s_mov_b32 s35, 0
	v_lshl_add_u64 v[90:91], v[82:83], 0, s[34:35]
	s_ashr_i32 s24, s3, 11
	s_and_b32 s22, s3, 63
	s_lshl_b32 s36, s24, 12
	s_lshl_b32 s38, s22, 6
	s_or_b32 s36, s36, s38
	v_or_b32_e32 v122, s36, v164
	v_mov_b32_e32 v123, 0
	v_lshlrev_b64 v[122:123], 10, v[122:123]
	v_lshl_add_u64 v[120:121], v[90:91], 0, v[122:123]
	s_mov_b32 s26, 0x8000
	s_mov_b32 s27, 0
	s_mov_b32 s28, 0x400000
	s_mov_b32 s29, 0
	s_mov_b32 s37, 0
	global_load_dwordx4 v[104:107], v[120:121], off
	v_lshl_add_u64 v[122:123], v[120:121], 0, s[26:27]
	global_load_dwordx4 v[108:111], v[122:123], off
	s_waitcnt vmcnt(0)
.Lssm2_task:
	s_waitcnt vmcnt(2)
	v_mov_b32_e32 v100, v104
	v_mov_b32_e32 v101, v105
	v_mov_b32_e32 v102, v106
	v_mov_b32_e32 v103, v107
	v_mov_b32_e32 v112, v108
	v_mov_b32_e32 v113, v109
	v_mov_b32_e32 v114, v110
	v_mov_b32_e32 v115, v111
	v_lshl_add_u64 v[120:121], v[120:121], 0, s[28:29]
	global_load_dwordx4 v[104:107], v[120:121], off
	v_lshl_add_u64 v[122:123], v[120:121], 0, s[26:27]
	global_load_dwordx4 v[108:111], v[122:123], off
	v_mov_b32_e32 v116, 0
	v_mov_b32_e32 v117, 0
	v_mfma_f32_32x32x16_bf16 v[16:31], v[100:103], v[76:79], 0
	v_mfma_f32_32x32x16_bf16 v[32:47], v[100:103], v[64:67], 0
	v_mfma_f32_32x32x16_bf16 v[0:15], v[100:103], v[68:71], 0
	v_mfma_f32_32x32x16_bf16 v[48:63], v[100:103], v[72:75], 0
	s_nop 9
	v_permlane32_swap_b32_e32 v16, v32
	v_permlane32_swap_b32_e32 v17, v33
	v_permlane32_swap_b32_e32 v18, v34
	v_permlane32_swap_b32_e32 v19, v35
	v_permlane32_swap_b32_e32 v20, v36
	v_permlane32_swap_b32_e32 v21, v37
	v_permlane32_swap_b32_e32 v22, v38
	v_permlane32_swap_b32_e32 v23, v39
	v_permlane32_swap_b32_e32 v24, v40
	v_permlane32_swap_b32_e32 v25, v41
	v_permlane32_swap_b32_e32 v26, v42
	v_permlane32_swap_b32_e32 v27, v43
	v_permlane32_swap_b32_e32 v28, v44
	v_permlane32_swap_b32_e32 v29, v45
	v_permlane32_swap_b32_e32 v30, v46
	v_permlane32_swap_b32_e32 v31, v47
	v_permlane32_swap_b32_e32 v0, v48
	v_permlane32_swap_b32_e32 v1, v49
	v_permlane32_swap_b32_e32 v2, v50
	v_permlane32_swap_b32_e32 v3, v51
	v_permlane32_swap_b32_e32 v4, v52
	v_permlane32_swap_b32_e32 v5, v53
	v_permlane32_swap_b32_e32 v6, v54
	v_permlane32_swap_b32_e32 v7, v55
	v_permlane32_swap_b32_e32 v8, v56
	v_permlane32_swap_b32_e32 v9, v57
	v_permlane32_swap_b32_e32 v10, v58
	v_permlane32_swap_b32_e32 v11, v59
	v_permlane32_swap_b32_e32 v12, v60
	v_permlane32_swap_b32_e32 v13, v61
	v_permlane32_swap_b32_e32 v14, v62
	v_permlane32_swap_b32_e32 v15, v63
	v_fma_f32 v118, -v88, v117, v16
	v_fma_f32 v119, v88, v116, v0
	v_fma_f32 v116, v86, v116, v118
	v_fma_f32 v117, v86, v117, v119
	v_fma_f32 v118, -v88, v117, v17
	v_fma_f32 v119, v88, v116, v1
	v_fma_f32 v116, v86, v116, v118
	v_fma_f32 v117, v86, v117, v119
	v_fma_f32 v118, -v88, v117, v18
	v_fma_f32 v119, v88, v116, v2
	v_fma_f32 v116, v86, v116, v118
	v_fma_f32 v117, v86, v117, v119
	v_fma_f32 v118, -v88, v117, v19
	v_fma_f32 v119, v88, v116, v3
	v_fma_f32 v116, v86, v116, v118
	v_fma_f32 v117, v86, v117, v119
	v_fma_f32 v118, -v88, v117, v32
	v_fma_f32 v119, v88, v116, v48
	v_fma_f32 v116, v86, v116, v118
	v_fma_f32 v117, v86, v117, v119
	v_fma_f32 v118, -v88, v117, v33
	v_fma_f32 v119, v88, v116, v49
	v_fma_f32 v116, v86, v116, v118
	v_fma_f32 v117, v86, v117, v119
	v_fma_f32 v118, -v88, v117, v34
	v_fma_f32 v119, v88, v116, v50
	v_fma_f32 v116, v86, v116, v118
	v_fma_f32 v117, v86, v117, v119
	v_fma_f32 v118, -v88, v117, v35
	v_fma_f32 v119, v88, v116, v51
	v_fma_f32 v116, v86, v116, v118
	v_fma_f32 v117, v86, v117, v119
	v_fma_f32 v118, -v88, v117, v20
	v_fma_f32 v119, v88, v116, v4
	v_fma_f32 v116, v86, v116, v118
	v_fma_f32 v117, v86, v117, v119
	v_fma_f32 v118, -v88, v117, v21
	v_fma_f32 v119, v88, v116, v5
	v_fma_f32 v116, v86, v116, v118
	v_fma_f32 v117, v86, v117, v119
	v_fma_f32 v118, -v88, v117, v22
	v_fma_f32 v119, v88, v116, v6
	v_fma_f32 v116, v86, v116, v118
	v_fma_f32 v117, v86, v117, v119
	v_fma_f32 v118, -v88, v117, v23
	v_fma_f32 v119, v88, v116, v7
	v_fma_f32 v116, v86, v116, v118
	v_fma_f32 v117, v86, v117, v119
	v_fma_f32 v118, -v88, v117, v36
	v_fma_f32 v119, v88, v116, v52
	v_fma_f32 v116, v86, v116, v118
	v_fma_f32 v117, v86, v117, v119
	v_fma_f32 v118, -v88, v117, v37
	v_fma_f32 v119, v88, v116, v53
	v_fma_f32 v116, v86, v116, v118
	v_fma_f32 v117, v86, v117, v119
	v_fma_f32 v118, -v88, v117, v38
	v_fma_f32 v119, v88, v116, v54
	v_fma_f32 v116, v86, v116, v118
	v_fma_f32 v117, v86, v117, v119
	v_fma_f32 v118, -v88, v117, v39
	v_fma_f32 v119, v88, v116, v55
	v_fma_f32 v116, v86, v116, v118
	v_fma_f32 v117, v86, v117, v119
	v_fma_f32 v118, -v88, v117, v24
	v_fma_f32 v119, v88, v116, v8
	v_fma_f32 v116, v86, v116, v118
	v_fma_f32 v117, v86, v117, v119
	v_fma_f32 v118, -v88, v117, v25
	v_fma_f32 v119, v88, v116, v9
	v_fma_f32 v116, v86, v116, v118
	v_fma_f32 v117, v86, v117, v119
	v_fma_f32 v118, -v88, v117, v26
	v_fma_f32 v119, v88, v116, v10
	v_fma_f32 v116, v86, v116, v118
	v_fma_f32 v117, v86, v117, v119
	v_fma_f32 v118, -v88, v117, v27
	v_fma_f32 v119, v88, v116, v11
	v_fma_f32 v116, v86, v116, v118
	v_fma_f32 v117, v86, v117, v119
	v_fma_f32 v118, -v88, v117, v40
	v_fma_f32 v119, v88, v116, v56
	v_fma_f32 v116, v86, v116, v118
	v_fma_f32 v117, v86, v117, v119
	v_fma_f32 v118, -v88, v117, v41
	v_fma_f32 v119, v88, v116, v57
	v_fma_f32 v116, v86, v116, v118
	v_fma_f32 v117, v86, v117, v119
	v_fma_f32 v118, -v88, v117, v42
	v_fma_f32 v119, v88, v116, v58
	v_fma_f32 v116, v86, v116, v118
	v_fma_f32 v117, v86, v117, v119
	v_fma_f32 v118, -v88, v117, v43
	v_fma_f32 v119, v88, v116, v59
	v_fma_f32 v116, v86, v116, v118
	v_fma_f32 v117, v86, v117, v119
	v_fma_f32 v118, -v88, v117, v28
	v_fma_f32 v119, v88, v116, v12
	v_fma_f32 v116, v86, v116, v118
	v_fma_f32 v117, v86, v117, v119
	v_fma_f32 v118, -v88, v117, v29
	v_fma_f32 v119, v88, v116, v13
	v_fma_f32 v116, v86, v116, v118
	v_fma_f32 v117, v86, v117, v119
	v_fma_f32 v118, -v88, v117, v30
	v_fma_f32 v119, v88, v116, v14
	v_fma_f32 v116, v86, v116, v118
	v_fma_f32 v117, v86, v117, v119
	v_fma_f32 v118, -v88, v117, v31
	v_fma_f32 v119, v88, v116, v15
	v_fma_f32 v116, v86, v116, v118
	v_fma_f32 v117, v86, v117, v119
	v_fma_f32 v118, -v88, v117, v44
	v_fma_f32 v119, v88, v116, v60
	v_fma_f32 v116, v86, v116, v118
	v_fma_f32 v117, v86, v117, v119
	v_fma_f32 v118, -v88, v117, v45
	v_fma_f32 v119, v88, v116, v61
	v_fma_f32 v116, v86, v116, v118
	v_fma_f32 v117, v86, v117, v119
	v_fma_f32 v118, -v88, v117, v46
	v_fma_f32 v119, v88, v116, v62
	v_fma_f32 v116, v86, v116, v118
	v_fma_f32 v117, v86, v117, v119
	v_fma_f32 v118, -v88, v117, v47
	v_fma_f32 v119, v88, v116, v63
	v_fma_f32 v116, v86, v116, v118
	v_fma_f32 v117, v86, v117, v119
	v_mfma_f32_32x32x16_bf16 v[16:31], v[112:115], v[76:79], 0
	v_mfma_f32_32x32x16_bf16 v[32:47], v[112:115], v[64:67], 0
	v_mfma_f32_32x32x16_bf16 v[0:15], v[112:115], v[68:71], 0
	v_mfma_f32_32x32x16_bf16 v[48:63], v[112:115], v[72:75], 0
	s_nop 9
	v_permlane32_swap_b32_e32 v16, v32
	v_permlane32_swap_b32_e32 v17, v33
	v_permlane32_swap_b32_e32 v18, v34
	v_permlane32_swap_b32_e32 v19, v35
	v_permlane32_swap_b32_e32 v20, v36
	v_permlane32_swap_b32_e32 v21, v37
	v_permlane32_swap_b32_e32 v22, v38
	v_permlane32_swap_b32_e32 v23, v39
	v_permlane32_swap_b32_e32 v24, v40
	v_permlane32_swap_b32_e32 v25, v41
	v_permlane32_swap_b32_e32 v26, v42
	v_permlane32_swap_b32_e32 v27, v43
	v_permlane32_swap_b32_e32 v28, v44
	v_permlane32_swap_b32_e32 v29, v45
	v_permlane32_swap_b32_e32 v30, v46
	v_permlane32_swap_b32_e32 v31, v47
	v_permlane32_swap_b32_e32 v0, v48
	v_permlane32_swap_b32_e32 v1, v49
	v_permlane32_swap_b32_e32 v2, v50
	v_permlane32_swap_b32_e32 v3, v51
	v_permlane32_swap_b32_e32 v4, v52
	v_permlane32_swap_b32_e32 v5, v53
	v_permlane32_swap_b32_e32 v6, v54
	v_permlane32_swap_b32_e32 v7, v55
	v_permlane32_swap_b32_e32 v8, v56
	v_permlane32_swap_b32_e32 v9, v57
	v_permlane32_swap_b32_e32 v10, v58
	v_permlane32_swap_b32_e32 v11, v59
	v_permlane32_swap_b32_e32 v12, v60
	v_permlane32_swap_b32_e32 v13, v61
	v_permlane32_swap_b32_e32 v14, v62
	v_permlane32_swap_b32_e32 v15, v63
	v_fma_f32 v118, -v88, v117, v16
	v_fma_f32 v119, v88, v116, v0
	v_fma_f32 v116, v86, v116, v118
	v_fma_f32 v117, v86, v117, v119
	v_fma_f32 v118, -v88, v117, v17
	v_fma_f32 v119, v88, v116, v1
	v_fma_f32 v116, v86, v116, v118
	v_fma_f32 v117, v86, v117, v119
	v_fma_f32 v118, -v88, v117, v18
	v_fma_f32 v119, v88, v116, v2
	v_fma_f32 v116, v86, v116, v118
	v_fma_f32 v117, v86, v117, v119
	v_fma_f32 v118, -v88, v117, v19
	v_fma_f32 v119, v88, v116, v3
	v_fma_f32 v116, v86, v116, v118
	v_fma_f32 v117, v86, v117, v119
	v_fma_f32 v118, -v88, v117, v32
	v_fma_f32 v119, v88, v116, v48
	v_fma_f32 v116, v86, v116, v118
	v_fma_f32 v117, v86, v117, v119
	v_fma_f32 v118, -v88, v117, v33
	v_fma_f32 v119, v88, v116, v49
	v_fma_f32 v116, v86, v116, v118
	v_fma_f32 v117, v86, v117, v119
	v_fma_f32 v118, -v88, v117, v34
	v_fma_f32 v119, v88, v116, v50
	v_fma_f32 v116, v86, v116, v118
	v_fma_f32 v117, v86, v117, v119
	v_fma_f32 v118, -v88, v117, v35
	v_fma_f32 v119, v88, v116, v51
	v_fma_f32 v116, v86, v116, v118
	v_fma_f32 v117, v86, v117, v119
	v_fma_f32 v118, -v88, v117, v20
	v_fma_f32 v119, v88, v116, v4
	v_fma_f32 v116, v86, v116, v118
	v_fma_f32 v117, v86, v117, v119
	v_fma_f32 v118, -v88, v117, v21
	v_fma_f32 v119, v88, v116, v5
	v_fma_f32 v116, v86, v116, v118
	v_fma_f32 v117, v86, v117, v119
	v_fma_f32 v118, -v88, v117, v22
	v_fma_f32 v119, v88, v116, v6
	v_fma_f32 v116, v86, v116, v118
	v_fma_f32 v117, v86, v117, v119
	v_fma_f32 v118, -v88, v117, v23
	v_fma_f32 v119, v88, v116, v7
	v_fma_f32 v116, v86, v116, v118
	v_fma_f32 v117, v86, v117, v119
	v_fma_f32 v118, -v88, v117, v36
	v_fma_f32 v119, v88, v116, v52
	v_fma_f32 v116, v86, v116, v118
	v_fma_f32 v117, v86, v117, v119
	v_fma_f32 v118, -v88, v117, v37
	v_fma_f32 v119, v88, v116, v53
	v_fma_f32 v116, v86, v116, v118
	v_fma_f32 v117, v86, v117, v119
	v_fma_f32 v118, -v88, v117, v38
	v_fma_f32 v119, v88, v116, v54
	v_fma_f32 v116, v86, v116, v118
	v_fma_f32 v117, v86, v117, v119
	v_fma_f32 v118, -v88, v117, v39
	v_fma_f32 v119, v88, v116, v55
	v_fma_f32 v116, v86, v116, v118
	v_fma_f32 v117, v86, v117, v119
	v_fma_f32 v118, -v88, v117, v24
	v_fma_f32 v119, v88, v116, v8
	v_fma_f32 v116, v86, v116, v118
	v_fma_f32 v117, v86, v117, v119
	v_fma_f32 v118, -v88, v117, v25
	v_fma_f32 v119, v88, v116, v9
	v_fma_f32 v116, v86, v116, v118
	v_fma_f32 v117, v86, v117, v119
	v_fma_f32 v118, -v88, v117, v26
	v_fma_f32 v119, v88, v116, v10
	v_fma_f32 v116, v86, v116, v118
	v_fma_f32 v117, v86, v117, v119
	v_fma_f32 v118, -v88, v117, v27
	v_fma_f32 v119, v88, v116, v11
	v_fma_f32 v116, v86, v116, v118
	v_fma_f32 v117, v86, v117, v119
	v_fma_f32 v118, -v88, v117, v40
	v_fma_f32 v119, v88, v116, v56
	v_fma_f32 v116, v86, v116, v118
	v_fma_f32 v117, v86, v117, v119
	v_fma_f32 v118, -v88, v117, v41
	v_fma_f32 v119, v88, v116, v57
	v_fma_f32 v116, v86, v116, v118
	v_fma_f32 v117, v86, v117, v119
	v_fma_f32 v118, -v88, v117, v42
	v_fma_f32 v119, v88, v116, v58
	v_fma_f32 v116, v86, v116, v118
	v_fma_f32 v117, v86, v117, v119
	v_fma_f32 v118, -v88, v117, v43
	v_fma_f32 v119, v88, v116, v59
	v_fma_f32 v116, v86, v116, v118
	v_fma_f32 v117, v86, v117, v119
	v_fma_f32 v118, -v88, v117, v28
	v_fma_f32 v119, v88, v116, v12
	v_fma_f32 v116, v86, v116, v118
	v_fma_f32 v117, v86, v117, v119
	v_fma_f32 v118, -v88, v117, v29
	v_fma_f32 v119, v88, v116, v13
	v_fma_f32 v116, v86, v116, v118
	v_fma_f32 v117, v86, v117, v119
	v_fma_f32 v118, -v88, v117, v30
	v_fma_f32 v119, v88, v116, v14
	v_fma_f32 v116, v86, v116, v118
	v_fma_f32 v117, v86, v117, v119
	v_fma_f32 v118, -v88, v117, v31
	v_fma_f32 v119, v88, v116, v15
	v_fma_f32 v116, v86, v116, v118
	v_fma_f32 v117, v86, v117, v119
	v_fma_f32 v118, -v88, v117, v44
	v_fma_f32 v119, v88, v116, v60
	v_fma_f32 v116, v86, v116, v118
	v_fma_f32 v117, v86, v117, v119
	v_fma_f32 v118, -v88, v117, v45
	v_fma_f32 v119, v88, v116, v61
	v_fma_f32 v116, v86, v116, v118
	v_fma_f32 v117, v86, v117, v119
	v_fma_f32 v118, -v88, v117, v46
	v_fma_f32 v119, v88, v116, v62
	v_fma_f32 v116, v86, v116, v118
	v_fma_f32 v117, v86, v117, v119
	v_fma_f32 v118, -v88, v117, v47
	v_fma_f32 v119, v88, v116, v63
	v_fma_f32 v116, v86, v116, v118
	v_fma_f32 v117, v86, v117, v119
	s_ashr_i32 s24, s3, 11
	s_and_b32 s22, s3, 63
	s_lshl_b32 s36, s24, 11
	s_or_b32 s36, s36, s30
	s_or_b32 s36, s36, s22
	s_lshl_b32 s36, s36, 9
	v_lshl_add_u64 v[0:1], v[84:85], 0, s[36:37]
	s_add_i32 s3, s3, s87
	s_cmpk_gt_i32 s3, 0x3fff
	global_store_dword v[0:1], v116, off
	global_store_dword v[0:1], v117, off offset:256
	s_cbranch_scc0 .Lssm2_task

.LBB0_209:
	s_bfe_u32 s14, s77, 0x30005
	s_lshl_b32 s15, s14, 22
	s_add_u32 s18, s31, s15
	s_addc_u32 s19, s34, 0
	s_and_b32 s12, s77, 7
	s_xor_b32 s22, s12, 15
	s_cmpk_lt_u32 s77, 0x100
	v_mov_b32_e32 v74, v165
	s_cselect_b32 s22, s12, s22
	s_bfe_u32 s24, s77, 0x20003
	v_readfirstlane_b32 s12, v74
	s_ashr_i32 s25, s12, 6
	s_lshl_b32 s29, s25, 3
	s_lshl_b32 s23, s25, 1
	s_or_b32 s53, s29, 4
	s_lshl_b32 s27, s14, 12
	s_lshl_b32 s26, s22, 2
	s_ashr_i32 s39, s12, 7
	s_lshl_b32 s12, s24, 8
	s_and_b32 s38, s23, 2
	s_bfe_u32 s54, s53, 0x20002
	s_lshl_b32 s55, s22, 8
	s_lshl_b32 s28, s14, 21
	s_add_u32 s22, s78, s15
	s_addc_u32 s23, s79, 0
	s_lshl_b32 s15, s25, 5
	s_or_b32 s14, s55, s27
	s_ashr_i32 s27, s15, 31
	s_add_u32 s14, s15, s14
	v_and_b32_e32 v168, 31, v74
	s_addc_u32 s15, s27, 0
	v_or_b32_e32 v0, s14, v168
	v_mov_b32_e32 v1, s15
	v_lshlrev_b64 v[0:1], 10, v[0:1]
	v_bfe_u32 v183, v74, 5, 1
	v_lshl_add_u64 v[0:1], s[46:47], 0, v[0:1]
	v_lshl_add_u64 v[0:1], v[0:1], 0, s[12:13]
	v_lshlrev_b32_e32 v166, 4, v183
	v_lshl_add_u64 v[0:1], v[0:1], 0, v[166:167]
	global_load_dwordx4 v[128:131], v[0:1], off offset:224
	global_load_dwordx4 v[132:135], v[0:1], off offset:192
	global_load_dwordx4 v[144:147], v[0:1], off offset:96
	global_load_dwordx4 v[148:151], v[0:1], off offset:64
	global_load_dwordx4 v[136:139], v[0:1], off offset:160
	global_load_dwordx4 v[140:143], v[0:1], off offset:128
	global_load_dwordx4 v[152:155], v[0:1], off offset:32
	global_load_dwordx4 v[156:159], v[0:1], off
	v_lshlrev_b32_e32 v2, 2, v74
	v_bfe_u32 v0, v74, 4, 2
	v_bfe_u32 v75, v74, 2, 2
	v_and_b32_e32 v2, 12, v2
	v_or_b32_e32 v5, 8, v183
	v_or_b32_e32 v76, 2, v183
	v_or_b32_e32 v6, 10, v183
	v_or_b32_e32 v7, 4, v183
	v_or_b32_e32 v8, 12, v183
	v_or_b32_e32 v9, 6, v183
	v_or_b32_e32 v10, 14, v183
	v_and_b32_e32 v1, 15, v74
	v_lshlrev_b32_e32 v3, 2, v0
	v_lshlrev_b32_e32 v4, 8, v168
	v_bitop3_b32 v11, v2, v183, v75 bitop3:0x36
	v_bitop3_b32 v5, v2, v5, v75 bitop3:0x36
	v_bitop3_b32 v12, v2, v76, v75 bitop3:0x36
	v_bitop3_b32 v6, v2, v6, v75 bitop3:0x36
	v_bitop3_b32 v7, v2, v7, v75 bitop3:0x36
	v_bitop3_b32 v8, v2, v8, v75 bitop3:0x36
	v_bitop3_b32 v9, v2, v9, v75 bitop3:0x36
	v_bitop3_b32 v2, v2, v10, v75 bitop3:0x36
	v_lshl_or_b32 v191, v11, 4, v4
	v_lshl_or_b32 v187, v5, 4, v4
	v_lshl_or_b32 v190, v12, 4, v4
	v_lshl_or_b32 v186, v6, 4, v4
	v_lshl_or_b32 v189, v7, 4, v4
	v_lshl_or_b32 v185, v8, 4, v4
	v_lshl_or_b32 v188, v9, 4, v4
	v_lshl_or_b32 v184, v2, 4, v4
	v_or_b32_e32 v2, s29, v0
	v_bitop3_b32 v4, s38, v1, v3 bitop3:0x36
	v_lshlrev_b32_e32 v2, 10, v2
	v_or_b32_e32 v0, s53, v0
	v_lshlrev_b32_e32 v4, 4, v4
	v_bitop3_b32 v1, s54, v1, v3 bitop3:0x36
	s_lshl_b32 s56, s25, 11
	v_lshlrev_b32_e32 v0, 10, v0
	v_or3_b32 v166, v4, v2, s12
	v_lshlrev_b32_e32 v1, 4, v1
	s_or_b32 s55, s56, 0x400
	v_mov_b32_e32 v171, v167
	v_or3_b32 v170, v1, v0, s12
	s_lshl_b32 s12, s24, 7
	s_add_i32 s39, s39, s26
	s_add_i32 s38, s56, 0
	s_add_i32 s57, s55, 0
	v_lshl_add_u64 v[70:71], s[22:23], 0, v[166:167]
	v_lshl_add_u64 v[64:65], s[22:23], 0, v[170:171]
	s_add_u32 s24, s22, 0x10000
	s_mov_b32 s27, 2
	v_mov_b32_e32 v72, v167
	v_mov_b32_e32 v73, v167
	s_mov_b32 s54, 0
	s_waitcnt vmcnt(0)
	s_mov_b32 vcc_hi, m0
	v_mov_b32_e32 v246, v242
	v_mov_b32_e32 v247, v243
	v_lshrrev_b32_e32 v0, 3, v74
	v_and_b32_e32 v0, 2, v0
	v_bfe_u32 v1, v74, 1, 1
	v_lshlrev_b32_e32 v3, 3, v74
	v_lshlrev_b32_e32 v4, 8, v75
	v_bitop3_b32 v5, v0, v183, v1 bitop3:0x36
	v_bitop3_b32 v0, v76, v0, v1 bitop3:0x1e
	v_and_b32_e32 v3, 8, v3
	v_lshl_or_b32 v4, v183, 10, v4
	v_lshlrev_b32_e32 v0, 4, v0
	v_or3_b32 v6, v0, v4, v3
	v_lshlrev_b32_e32 v5, 4, v5
	v_or3_b32 v7, v5, v4, v3
	v_lshlrev_b32_e32 v8, 6, v75
	v_add_u32_e32 v7, 0xc000, v7
	v_add_u32_e32 v6, 0xc800, v6
	v_mov_b32_e32 v9, v8
	v_add_u32_e32 v172, v7, v9
	v_add_u32_e32 v192, v6, v9
	v_xor_b32_e32 v9, 0x40, v8
	v_add_u32_e32 v173, v7, v9
	v_add_u32_e32 v193, v6, v9
	v_xor_b32_e32 v9, 0x80, v8
	v_add_u32_e32 v174, v7, v9
	v_add_u32_e32 v194, v6, v9
	v_xor_b32_e32 v9, 0xc0, v8
	v_add_u32_e32 v175, v7, v9
	v_add_u32_e32 v197, v6, v9
	s_or_b32 s53, s26, 2
	s_add_i32 s29, s26, 4
	s_add_i32 vcc_lo, s39, 1
	v_mov_b32_e32 v0, 0
	v_mov_b32_e32 v1, 0
	v_mov_b32_e32 v2, 0
	v_mov_b32_e32 v3, 0
	v_mov_b32_e32 v4, 0
	v_mov_b32_e32 v5, 0
	v_mov_b32_e32 v6, 0
	v_mov_b32_e32 v7, 0
	v_mov_b32_e32 v8, 0
	v_mov_b32_e32 v9, 0
	v_mov_b32_e32 v10, 0
	v_mov_b32_e32 v11, 0
	v_mov_b32_e32 v12, 0
	v_mov_b32_e32 v13, 0
	v_mov_b32_e32 v14, 0
	v_mov_b32_e32 v15, 0
	v_mov_b32_e32 v16, 0
	v_mov_b32_e32 v17, 0
	v_mov_b32_e32 v18, 0
	v_mov_b32_e32 v19, 0
	v_mov_b32_e32 v20, 0
	v_mov_b32_e32 v21, 0
	v_mov_b32_e32 v22, 0
	v_mov_b32_e32 v23, 0
	v_mov_b32_e32 v24, 0
	v_mov_b32_e32 v25, 0
	v_mov_b32_e32 v26, 0
	v_mov_b32_e32 v27, 0
	v_mov_b32_e32 v28, 0
	v_mov_b32_e32 v29, 0
	v_mov_b32_e32 v30, 0
	v_mov_b32_e32 v31, 0
	v_mov_b32_e32 v32, 0
	v_mov_b32_e32 v33, 0
	v_mov_b32_e32 v34, 0
	v_mov_b32_e32 v35, 0
	v_mov_b32_e32 v36, 0
	v_mov_b32_e32 v37, 0
	v_mov_b32_e32 v38, 0
	v_mov_b32_e32 v39, 0
	v_mov_b32_e32 v40, 0
	v_mov_b32_e32 v41, 0
	v_mov_b32_e32 v42, 0
	v_mov_b32_e32 v43, 0
	v_mov_b32_e32 v44, 0
	v_mov_b32_e32 v45, 0
	v_mov_b32_e32 v46, 0
	v_mov_b32_e32 v47, 0
	v_mov_b32_e32 v48, 0
	v_mov_b32_e32 v49, 0
	v_mov_b32_e32 v50, 0
	v_mov_b32_e32 v51, 0
	v_mov_b32_e32 v52, 0
	v_mov_b32_e32 v53, 0
	v_mov_b32_e32 v54, 0
	v_mov_b32_e32 v55, 0
	v_mov_b32_e32 v56, 0
	v_mov_b32_e32 v57, 0
	v_mov_b32_e32 v58, 0
	v_mov_b32_e32 v59, 0
	v_mov_b32_e32 v60, 0
	v_mov_b32_e32 v61, 0
	v_mov_b32_e32 v62, 0
	v_mov_b32_e32 v63, 0
	s_mov_b64 s[24:25], s[22:23]
	s_add_u32 s58, s22, 0x2000000
	s_addc_u32 s59, s23, 0
	s_mov_b32 m0, s38
	s_nop 0
	global_load_lds_dwordx4 v166, s[24:25]
	s_mov_b32 m0, s57
	s_nop 0
	global_load_lds_dwordx4 v170, s[24:25]
	s_add_u32 s24, s24, 0x10000
	s_addc_u32 s25, s25, 0
	s_add_i32 m0, s38, 0xc000
	s_nop 0
	global_load_lds_dwordx4 v166, s[58:59]
	s_add_i32 m0, s57, 0xc000
	s_nop 0
	global_load_lds_dwordx4 v170, s[58:59]
	s_add_u32 s58, s58, 0x10000
	s_addc_u32 s59, s59, 0
	s_add_i32 m0, s38, 0x4000
	s_nop 0
	global_load_lds_dwordx4 v166, s[24:25]
	s_add_i32 m0, s57, 0x4000
	s_nop 0
	global_load_lds_dwordx4 v170, s[24:25]
	s_add_u32 s24, s24, 0x10000
	s_addc_u32 s25, s25, 0
	s_mov_b32 s54, 0
	v_mov_b32_e32 v198, 0
	v_mov_b32_e32 v199, 0
	v_mov_b32_e32 v200, 0
	v_mov_b32_e32 v201, 0

.Lpa_w1_0:
	s_barrier
	s_cmp_lt_i32 s54, s29
	s_cbranch_scc0 .Lpa_nodma_0
	s_add_i32 m0, s38, 0x10000
	s_nop 0
	global_load_lds_dwordx4 v166, s[58:59]
	s_add_i32 m0, s57, 0x10000
	s_nop 0
	global_load_lds_dwordx4 v170, s[58:59]
	s_add_u32 s58, s58, 0x10000
	s_addc_u32 s59, s59, 0
	s_cmp_gt_i32 s54, s53
	s_cbranch_scc1 .Lpa_nodma_0
	s_add_i32 m0, s38, 0x8000
	s_nop 0
	global_load_lds_dwordx4 v166, s[24:25]
	s_add_i32 m0, s57, 0x8000
	s_nop 0
	global_load_lds_dwordx4 v170, s[24:25]
	s_add_u32 s24, s24, 0x10000
	s_addc_u32 s25, s25, 0
.Lpa_nodma_0:
	s_cmp_gt_i32 s54, vcc_lo
	s_cbranch_scc1 .Lpa_next_0
	s_cmp_eq_u32 s54, 1
	s_cbranch_scc0 .Lpa_pend_0
	ds_read_b128 v[96:99], v191 offset:0
	ds_read_b128 v[100:103], v190 offset:0
	ds_read_b128 v[104:107], v189 offset:0
	ds_read_b128 v[108:111], v188 offset:0
	s_waitcnt lgkmcnt(3)
	v_mfma_f32_32x32x16_bf16 v[64:79], v[96:99], v[156:159], 0
	s_waitcnt lgkmcnt(2)
	v_mfma_f32_32x32x16_bf16 v[64:79], v[100:103], v[152:155], v[64:79]
	s_waitcnt lgkmcnt(1)
	v_mfma_f32_32x32x16_bf16 v[64:79], v[104:107], v[148:151], v[64:79]
	s_waitcnt lgkmcnt(0)
	v_mfma_f32_32x32x16_bf16 v[64:79], v[108:111], v[144:147], v[64:79]
	s_nop 11
	v_exp_f32_e32 v64, v64
	v_exp_f32_e32 v65, v65
	v_exp_f32_e32 v66, v66
	v_exp_f32_e32 v67, v67
	v_pk_add_f32 v[198:199], v[198:199], v[64:65]
	v_pk_add_f32 v[200:201], v[200:201], v[66:67]
	v_exp_f32_e32 v68, v68
	v_exp_f32_e32 v69, v69
	v_exp_f32_e32 v70, v70
	v_exp_f32_e32 v71, v71
	v_pk_add_f32 v[198:199], v[198:199], v[68:69]
	v_pk_add_f32 v[200:201], v[200:201], v[70:71]
	v_exp_f32_e32 v72, v72
	v_exp_f32_e32 v73, v73
	v_exp_f32_e32 v74, v74
	v_exp_f32_e32 v75, v75
	v_pk_add_f32 v[198:199], v[198:199], v[72:73]
	v_pk_add_f32 v[200:201], v[200:201], v[74:75]
	v_exp_f32_e32 v76, v76
	v_exp_f32_e32 v77, v77
	v_exp_f32_e32 v78, v78
	v_exp_f32_e32 v79, v79
	v_pk_add_f32 v[198:199], v[198:199], v[76:77]
	v_pk_add_f32 v[200:201], v[200:201], v[78:79]
	v_cvt_pk_bf16_f32 v80, v64, v65
	v_cvt_pk_bf16_f32 v81, v66, v67
	v_cvt_pk_bf16_f32 v82, v68, v69
	v_cvt_pk_bf16_f32 v83, v70, v71
	v_cvt_pk_bf16_f32 v84, v72, v73
	v_cvt_pk_bf16_f32 v85, v74, v75
	v_cvt_pk_bf16_f32 v86, v76, v77
	v_cvt_pk_bf16_f32 v87, v78, v79
	s_branch .Lpa_h1_0
.Lpa_pend_0:
	ds_read_b128 v[96:99], v191 offset:0
	ds_read_b128 v[100:103], v190 offset:0
	ds_read_b128 v[104:107], v189 offset:0
	ds_read_b128 v[108:111], v188 offset:0
	ds_read_b64_tr_b16 v[112:113], v172 offset:40960
	ds_read_b64_tr_b16 v[114:115], v192 offset:40960
	ds_read_b64_tr_b16 v[116:117], v173 offset:40960
	ds_read_b64_tr_b16 v[118:119], v193 offset:40960
	ds_read_b64_tr_b16 v[120:121], v174 offset:40960
	ds_read_b64_tr_b16 v[122:123], v194 offset:40960
	ds_read_b64_tr_b16 v[124:125], v175 offset:40960
	ds_read_b64_tr_b16 v[126:127], v197 offset:40960
	s_waitcnt lgkmcnt(11)
	v_mfma_f32_32x32x16_bf16 v[64:79], v[96:99], v[156:159], 0
	s_waitcnt lgkmcnt(10)
	v_mfma_f32_32x32x16_bf16 v[64:79], v[100:103], v[152:155], v[64:79]
	s_waitcnt lgkmcnt(9)
	v_mfma_f32_32x32x16_bf16 v[64:79], v[104:107], v[148:151], v[64:79]
	s_waitcnt lgkmcnt(8)
	v_mfma_f32_32x32x16_bf16 v[64:79], v[108:111], v[144:147], v[64:79]
	s_waitcnt lgkmcnt(6)
	v_mfma_f32_32x32x16_bf16 v[0:15], v[88:91], v[112:115], v[0:15]
	ds_read_b64_tr_b16 v[112:113], v172 offset:45056
	ds_read_b64_tr_b16 v[114:115], v192 offset:45056
	s_waitcnt lgkmcnt(6)
	v_mfma_f32_32x32x16_bf16 v[16:31], v[88:91], v[116:119], v[16:31]
	ds_read_b64_tr_b16 v[116:117], v173 offset:45056
	ds_read_b64_tr_b16 v[118:119], v193 offset:45056
	s_waitcnt lgkmcnt(6)
	v_mfma_f32_32x32x16_bf16 v[32:47], v[88:91], v[120:123], v[32:47]
	ds_read_b64_tr_b16 v[120:121], v174 offset:45056
	ds_read_b64_tr_b16 v[122:123], v194 offset:45056
	v_exp_f32_e32 v64, v64
	v_exp_f32_e32 v65, v65
	v_exp_f32_e32 v66, v66
	v_exp_f32_e32 v67, v67
	v_pk_add_f32 v[198:199], v[198:199], v[64:65]
	v_pk_add_f32 v[200:201], v[200:201], v[66:67]
	s_waitcnt lgkmcnt(6)
	v_mfma_f32_32x32x16_bf16 v[48:63], v[88:91], v[124:127], v[48:63]
	ds_read_b64_tr_b16 v[124:125], v175 offset:45056
	ds_read_b64_tr_b16 v[126:127], v197 offset:45056
	v_exp_f32_e32 v68, v68
	v_exp_f32_e32 v69, v69
	v_exp_f32_e32 v70, v70
	v_exp_f32_e32 v71, v71
	v_pk_add_f32 v[198:199], v[198:199], v[68:69]
	v_pk_add_f32 v[200:201], v[200:201], v[70:71]
	s_waitcnt lgkmcnt(6)
	v_mfma_f32_32x32x16_bf16 v[0:15], v[92:95], v[112:115], v[0:15]
	v_exp_f32_e32 v72, v72
	v_exp_f32_e32 v73, v73
	v_exp_f32_e32 v74, v74
	v_exp_f32_e32 v75, v75
	v_pk_add_f32 v[198:199], v[198:199], v[72:73]
	v_pk_add_f32 v[200:201], v[200:201], v[74:75]
	s_waitcnt lgkmcnt(4)
	v_mfma_f32_32x32x16_bf16 v[16:31], v[92:95], v[116:119], v[16:31]
	v_exp_f32_e32 v76, v76
	v_exp_f32_e32 v77, v77
	v_exp_f32_e32 v78, v78
	v_exp_f32_e32 v79, v79
	v_pk_add_f32 v[198:199], v[198:199], v[76:77]
	v_pk_add_f32 v[200:201], v[200:201], v[78:79]
	s_waitcnt lgkmcnt(2)
	v_mfma_f32_32x32x16_bf16 v[32:47], v[92:95], v[120:123], v[32:47]
	v_cvt_pk_bf16_f32 v80, v64, v65
	v_cvt_pk_bf16_f32 v81, v66, v67
	v_cvt_pk_bf16_f32 v82, v68, v69
	v_cvt_pk_bf16_f32 v83, v70, v71
	s_waitcnt lgkmcnt(0)
	v_mfma_f32_32x32x16_bf16 v[48:63], v[92:95], v[124:127], v[48:63]
	v_cvt_pk_bf16_f32 v84, v72, v73
	v_cvt_pk_bf16_f32 v85, v74, v75
	v_cvt_pk_bf16_f32 v86, v76, v77
	v_cvt_pk_bf16_f32 v87, v78, v79
.Lpa_h1_0:
	ds_read_b128 v[96:99], v191 offset:8192
	ds_read_b128 v[100:103], v190 offset:8192
	ds_read_b128 v[104:107], v189 offset:8192
	ds_read_b128 v[108:111], v188 offset:8192
	ds_read_b64_tr_b16 v[112:113], v172 offset:0
	ds_read_b64_tr_b16 v[114:115], v192 offset:0
	ds_read_b64_tr_b16 v[116:117], v173 offset:0
	ds_read_b64_tr_b16 v[118:119], v193 offset:0
	ds_read_b64_tr_b16 v[120:121], v174 offset:0
	ds_read_b64_tr_b16 v[122:123], v194 offset:0
	ds_read_b64_tr_b16 v[124:125], v175 offset:0
	ds_read_b64_tr_b16 v[126:127], v197 offset:0
	s_waitcnt lgkmcnt(11)
	v_mfma_f32_32x32x16_bf16 v[64:79], v[96:99], v[156:159], 0
	s_waitcnt lgkmcnt(10)
	v_mfma_f32_32x32x16_bf16 v[64:79], v[100:103], v[152:155], v[64:79]
	s_waitcnt lgkmcnt(9)
	v_mfma_f32_32x32x16_bf16 v[64:79], v[104:107], v[148:151], v[64:79]
	s_waitcnt lgkmcnt(8)
	v_mfma_f32_32x32x16_bf16 v[64:79], v[108:111], v[144:147], v[64:79]
	s_waitcnt lgkmcnt(6)
	v_mfma_f32_32x32x16_bf16 v[0:15], v[80:83], v[112:115], v[0:15]
	ds_read_b64_tr_b16 v[112:113], v172 offset:4096
	ds_read_b64_tr_b16 v[114:115], v192 offset:4096
	s_waitcnt lgkmcnt(6)
	v_mfma_f32_32x32x16_bf16 v[16:31], v[80:83], v[116:119], v[16:31]
	ds_read_b64_tr_b16 v[116:117], v173 offset:4096
	ds_read_b64_tr_b16 v[118:119], v193 offset:4096
	s_waitcnt lgkmcnt(6)
	v_mfma_f32_32x32x16_bf16 v[32:47], v[80:83], v[120:123], v[32:47]
	ds_read_b64_tr_b16 v[120:121], v174 offset:4096
	ds_read_b64_tr_b16 v[122:123], v194 offset:4096
	v_exp_f32_e32 v64, v64
	v_exp_f32_e32 v65, v65
	v_exp_f32_e32 v66, v66
	v_exp_f32_e32 v67, v67
	v_pk_add_f32 v[198:199], v[198:199], v[64:65]
	v_pk_add_f32 v[200:201], v[200:201], v[66:67]
	s_waitcnt lgkmcnt(6)
	v_mfma_f32_32x32x16_bf16 v[48:63], v[80:83], v[124:127], v[48:63]
	ds_read_b64_tr_b16 v[124:125], v175 offset:4096
	ds_read_b64_tr_b16 v[126:127], v197 offset:4096
	v_exp_f32_e32 v68, v68
	v_exp_f32_e32 v69, v69
	v_exp_f32_e32 v70, v70
	v_exp_f32_e32 v71, v71
	v_pk_add_f32 v[198:199], v[198:199], v[68:69]
	v_pk_add_f32 v[200:201], v[200:201], v[70:71]
	s_waitcnt lgkmcnt(6)
	v_mfma_f32_32x32x16_bf16 v[0:15], v[84:87], v[112:115], v[0:15]
	v_exp_f32_e32 v72, v72
	v_exp_f32_e32 v73, v73
	v_exp_f32_e32 v74, v74
	v_exp_f32_e32 v75, v75
	v_pk_add_f32 v[198:199], v[198:199], v[72:73]
	v_pk_add_f32 v[200:201], v[200:201], v[74:75]
	s_waitcnt lgkmcnt(4)
	v_mfma_f32_32x32x16_bf16 v[16:31], v[84:87], v[116:119], v[16:31]
	v_exp_f32_e32 v76, v76
	v_exp_f32_e32 v77, v77
	v_exp_f32_e32 v78, v78
	v_exp_f32_e32 v79, v79
	v_pk_add_f32 v[198:199], v[198:199], v[76:77]
	v_pk_add_f32 v[200:201], v[200:201], v[78:79]
	s_waitcnt lgkmcnt(2)
	v_mfma_f32_32x32x16_bf16 v[32:47], v[84:87], v[120:123], v[32:47]
	v_cvt_pk_bf16_f32 v88, v64, v65
	v_cvt_pk_bf16_f32 v89, v66, v67
	v_cvt_pk_bf16_f32 v90, v68, v69
	v_cvt_pk_bf16_f32 v91, v70, v71
	s_waitcnt lgkmcnt(0)
	v_mfma_f32_32x32x16_bf16 v[48:63], v[84:87], v[124:127], v[48:63]
	v_cvt_pk_bf16_f32 v92, v72, v73
	v_cvt_pk_bf16_f32 v93, v74, v75
	v_cvt_pk_bf16_f32 v94, v76, v77
	v_cvt_pk_bf16_f32 v95, v78, v79
	s_cmp_lt_i32 s54, vcc_lo
	s_cbranch_scc1 .Lpa_next_0
	s_nop 1
	ds_read_b64_tr_b16 v[112:113], v172 offset:8192
	ds_read_b64_tr_b16 v[114:115], v192 offset:8192
	ds_read_b64_tr_b16 v[116:117], v173 offset:8192
	ds_read_b64_tr_b16 v[118:119], v193 offset:8192
	ds_read_b64_tr_b16 v[120:121], v174 offset:8192
	ds_read_b64_tr_b16 v[122:123], v194 offset:8192
	ds_read_b64_tr_b16 v[124:125], v175 offset:8192
	ds_read_b64_tr_b16 v[126:127], v197 offset:8192
	s_waitcnt lgkmcnt(6)
	v_mfma_f32_32x32x16_bf16 v[0:15], v[88:91], v[112:115], v[0:15]
	ds_read_b64_tr_b16 v[112:113], v172 offset:12288
	ds_read_b64_tr_b16 v[114:115], v192 offset:12288
	s_waitcnt lgkmcnt(6)
	v_mfma_f32_32x32x16_bf16 v[16:31], v[88:91], v[116:119], v[16:31]
	ds_read_b64_tr_b16 v[116:117], v173 offset:12288
	ds_read_b64_tr_b16 v[118:119], v193 offset:12288
	s_waitcnt lgkmcnt(6)
	v_mfma_f32_32x32x16_bf16 v[32:47], v[88:91], v[120:123], v[32:47]
	ds_read_b64_tr_b16 v[120:121], v174 offset:12288
	ds_read_b64_tr_b16 v[122:123], v194 offset:12288
	s_waitcnt lgkmcnt(6)
	v_mfma_f32_32x32x16_bf16 v[48:63], v[88:91], v[124:127], v[48:63]
	ds_read_b64_tr_b16 v[124:125], v175 offset:12288
	ds_read_b64_tr_b16 v[126:127], v197 offset:12288
	s_waitcnt lgkmcnt(6)
	v_mfma_f32_32x32x16_bf16 v[0:15], v[92:95], v[112:115], v[0:15]
	s_waitcnt lgkmcnt(4)
	v_mfma_f32_32x32x16_bf16 v[16:31], v[92:95], v[116:119], v[16:31]
	s_waitcnt lgkmcnt(2)
	v_mfma_f32_32x32x16_bf16 v[32:47], v[92:95], v[120:123], v[32:47]
	s_waitcnt lgkmcnt(0)
	v_mfma_f32_32x32x16_bf16 v[48:63], v[92:95], v[124:127], v[48:63]
.Lpa_next_0:
	s_cmp_lt_i32 s54, s29
	s_cbranch_scc0 .Lpa_done

.Lpa_w1_1:
	s_barrier
	s_cmp_lt_i32 s54, s29
	s_cbranch_scc0 .Lpa_nodma_1
	s_add_i32 m0, s38, 0x14000
	s_nop 0
	global_load_lds_dwordx4 v166, s[58:59]
	s_add_i32 m0, s57, 0x14000
	s_nop 0
	global_load_lds_dwordx4 v170, s[58:59]
	s_add_u32 s58, s58, 0x10000
	s_addc_u32 s59, s59, 0
	s_cmp_gt_i32 s54, s53
	s_cbranch_scc1 .Lpa_nodma_1
	s_add_i32 m0, s38, 0x0
	s_nop 0
	global_load_lds_dwordx4 v166, s[24:25]
	s_add_i32 m0, s57, 0x0
	s_nop 0
	global_load_lds_dwordx4 v170, s[24:25]
	s_add_u32 s24, s24, 0x10000
	s_addc_u32 s25, s25, 0
.Lpa_nodma_1:
	s_cmp_gt_i32 s54, vcc_lo
	s_cbranch_scc1 .Lpa_next_1
	ds_read_b128 v[96:99], v191 offset:16384
	ds_read_b128 v[100:103], v190 offset:16384
	ds_read_b128 v[104:107], v189 offset:16384
	ds_read_b128 v[108:111], v188 offset:16384
	ds_read_b64_tr_b16 v[112:113], v172 offset:8192
	ds_read_b64_tr_b16 v[114:115], v192 offset:8192
	ds_read_b64_tr_b16 v[116:117], v173 offset:8192
	ds_read_b64_tr_b16 v[118:119], v193 offset:8192
	ds_read_b64_tr_b16 v[120:121], v174 offset:8192
	ds_read_b64_tr_b16 v[122:123], v194 offset:8192
	ds_read_b64_tr_b16 v[124:125], v175 offset:8192
	ds_read_b64_tr_b16 v[126:127], v197 offset:8192
	s_waitcnt lgkmcnt(11)
	v_mfma_f32_32x32x16_bf16 v[64:79], v[96:99], v[156:159], 0
	s_waitcnt lgkmcnt(10)
	v_mfma_f32_32x32x16_bf16 v[64:79], v[100:103], v[152:155], v[64:79]
	s_waitcnt lgkmcnt(9)
	v_mfma_f32_32x32x16_bf16 v[64:79], v[104:107], v[148:151], v[64:79]
	s_waitcnt lgkmcnt(8)
	v_mfma_f32_32x32x16_bf16 v[64:79], v[108:111], v[144:147], v[64:79]
	s_waitcnt lgkmcnt(6)
	v_mfma_f32_32x32x16_bf16 v[0:15], v[88:91], v[112:115], v[0:15]
	ds_read_b64_tr_b16 v[112:113], v172 offset:12288
	ds_read_b64_tr_b16 v[114:115], v192 offset:12288
	s_waitcnt lgkmcnt(6)
	v_mfma_f32_32x32x16_bf16 v[16:31], v[88:91], v[116:119], v[16:31]
	ds_read_b64_tr_b16 v[116:117], v173 offset:12288
	ds_read_b64_tr_b16 v[118:119], v193 offset:12288
	s_waitcnt lgkmcnt(6)
	v_mfma_f32_32x32x16_bf16 v[32:47], v[88:91], v[120:123], v[32:47]
	ds_read_b64_tr_b16 v[120:121], v174 offset:12288
	ds_read_b64_tr_b16 v[122:123], v194 offset:12288
	v_exp_f32_e32 v64, v64
	v_exp_f32_e32 v65, v65
	v_exp_f32_e32 v66, v66
	v_exp_f32_e32 v67, v67
	v_pk_add_f32 v[198:199], v[198:199], v[64:65]
	v_pk_add_f32 v[200:201], v[200:201], v[66:67]
	s_waitcnt lgkmcnt(6)
	v_mfma_f32_32x32x16_bf16 v[48:63], v[88:91], v[124:127], v[48:63]
	ds_read_b64_tr_b16 v[124:125], v175 offset:12288
	ds_read_b64_tr_b16 v[126:127], v197 offset:12288
	v_exp_f32_e32 v68, v68
	v_exp_f32_e32 v69, v69
	v_exp_f32_e32 v70, v70
	v_exp_f32_e32 v71, v71
	v_pk_add_f32 v[198:199], v[198:199], v[68:69]
	v_pk_add_f32 v[200:201], v[200:201], v[70:71]
	s_waitcnt lgkmcnt(6)
	v_mfma_f32_32x32x16_bf16 v[0:15], v[92:95], v[112:115], v[0:15]
	v_exp_f32_e32 v72, v72
	v_exp_f32_e32 v73, v73
	v_exp_f32_e32 v74, v74
	v_exp_f32_e32 v75, v75
	v_pk_add_f32 v[198:199], v[198:199], v[72:73]
	v_pk_add_f32 v[200:201], v[200:201], v[74:75]
	s_waitcnt lgkmcnt(4)
	v_mfma_f32_32x32x16_bf16 v[16:31], v[92:95], v[116:119], v[16:31]
	v_exp_f32_e32 v76, v76
	v_exp_f32_e32 v77, v77
	v_exp_f32_e32 v78, v78
	v_exp_f32_e32 v79, v79
	v_pk_add_f32 v[198:199], v[198:199], v[76:77]
	v_pk_add_f32 v[200:201], v[200:201], v[78:79]
	s_waitcnt lgkmcnt(2)
	v_mfma_f32_32x32x16_bf16 v[32:47], v[92:95], v[120:123], v[32:47]
	v_cvt_pk_bf16_f32 v80, v64, v65
	v_cvt_pk_bf16_f32 v81, v66, v67
	v_cvt_pk_bf16_f32 v82, v68, v69
	v_cvt_pk_bf16_f32 v83, v70, v71
	s_waitcnt lgkmcnt(0)
	v_mfma_f32_32x32x16_bf16 v[48:63], v[92:95], v[124:127], v[48:63]
	v_cvt_pk_bf16_f32 v84, v72, v73
	v_cvt_pk_bf16_f32 v85, v74, v75
	v_cvt_pk_bf16_f32 v86, v76, v77
	v_cvt_pk_bf16_f32 v87, v78, v79
.Lpa_h1_1:
	ds_read_b128 v[96:99], v191 offset:24576
	ds_read_b128 v[100:103], v190 offset:24576
	ds_read_b128 v[104:107], v189 offset:24576
	ds_read_b128 v[108:111], v188 offset:24576
	ds_read_b64_tr_b16 v[112:113], v172 offset:16384
	ds_read_b64_tr_b16 v[114:115], v192 offset:16384
	ds_read_b64_tr_b16 v[116:117], v173 offset:16384
	ds_read_b64_tr_b16 v[118:119], v193 offset:16384
	ds_read_b64_tr_b16 v[120:121], v174 offset:16384
	ds_read_b64_tr_b16 v[122:123], v194 offset:16384
	ds_read_b64_tr_b16 v[124:125], v175 offset:16384
	ds_read_b64_tr_b16 v[126:127], v197 offset:16384
	s_waitcnt lgkmcnt(11)
	v_mfma_f32_32x32x16_bf16 v[64:79], v[96:99], v[156:159], 0
	s_waitcnt lgkmcnt(10)
	v_mfma_f32_32x32x16_bf16 v[64:79], v[100:103], v[152:155], v[64:79]
	s_waitcnt lgkmcnt(9)
	v_mfma_f32_32x32x16_bf16 v[64:79], v[104:107], v[148:151], v[64:79]
	s_waitcnt lgkmcnt(8)
	v_mfma_f32_32x32x16_bf16 v[64:79], v[108:111], v[144:147], v[64:79]
	s_waitcnt lgkmcnt(6)
	v_mfma_f32_32x32x16_bf16 v[0:15], v[80:83], v[112:115], v[0:15]
	ds_read_b64_tr_b16 v[112:113], v172 offset:20480
	ds_read_b64_tr_b16 v[114:115], v192 offset:20480
	s_waitcnt lgkmcnt(6)
	v_mfma_f32_32x32x16_bf16 v[16:31], v[80:83], v[116:119], v[16:31]
	ds_read_b64_tr_b16 v[116:117], v173 offset:20480
	ds_read_b64_tr_b16 v[118:119], v193 offset:20480
	s_waitcnt lgkmcnt(6)
	v_mfma_f32_32x32x16_bf16 v[32:47], v[80:83], v[120:123], v[32:47]
	ds_read_b64_tr_b16 v[120:121], v174 offset:20480
	ds_read_b64_tr_b16 v[122:123], v194 offset:20480
	v_exp_f32_e32 v64, v64
	v_exp_f32_e32 v65, v65
	v_exp_f32_e32 v66, v66
	v_exp_f32_e32 v67, v67
	v_pk_add_f32 v[198:199], v[198:199], v[64:65]
	v_pk_add_f32 v[200:201], v[200:201], v[66:67]
	s_waitcnt lgkmcnt(6)
	v_mfma_f32_32x32x16_bf16 v[48:63], v[80:83], v[124:127], v[48:63]
	ds_read_b64_tr_b16 v[124:125], v175 offset:20480
	ds_read_b64_tr_b16 v[126:127], v197 offset:20480
	v_exp_f32_e32 v68, v68
	v_exp_f32_e32 v69, v69
	v_exp_f32_e32 v70, v70
	v_exp_f32_e32 v71, v71
	v_pk_add_f32 v[198:199], v[198:199], v[68:69]
	v_pk_add_f32 v[200:201], v[200:201], v[70:71]
	s_waitcnt lgkmcnt(6)
	v_mfma_f32_32x32x16_bf16 v[0:15], v[84:87], v[112:115], v[0:15]
	v_exp_f32_e32 v72, v72
	v_exp_f32_e32 v73, v73
	v_exp_f32_e32 v74, v74
	v_exp_f32_e32 v75, v75
	v_pk_add_f32 v[198:199], v[198:199], v[72:73]
	v_pk_add_f32 v[200:201], v[200:201], v[74:75]
	s_waitcnt lgkmcnt(4)
	v_mfma_f32_32x32x16_bf16 v[16:31], v[84:87], v[116:119], v[16:31]
	v_exp_f32_e32 v76, v76
	v_exp_f32_e32 v77, v77
	v_exp_f32_e32 v78, v78
	v_exp_f32_e32 v79, v79
	v_pk_add_f32 v[198:199], v[198:199], v[76:77]
	v_pk_add_f32 v[200:201], v[200:201], v[78:79]
	s_waitcnt lgkmcnt(2)
	v_mfma_f32_32x32x16_bf16 v[32:47], v[84:87], v[120:123], v[32:47]
	v_cvt_pk_bf16_f32 v88, v64, v65
	v_cvt_pk_bf16_f32 v89, v66, v67
	v_cvt_pk_bf16_f32 v90, v68, v69
	v_cvt_pk_bf16_f32 v91, v70, v71
	s_waitcnt lgkmcnt(0)
	v_mfma_f32_32x32x16_bf16 v[48:63], v[84:87], v[124:127], v[48:63]
	v_cvt_pk_bf16_f32 v92, v72, v73
	v_cvt_pk_bf16_f32 v93, v74, v75
	v_cvt_pk_bf16_f32 v94, v76, v77
	v_cvt_pk_bf16_f32 v95, v78, v79
	s_cmp_lt_i32 s54, vcc_lo
	s_cbranch_scc1 .Lpa_next_1
	s_nop 1
	ds_read_b64_tr_b16 v[112:113], v172 offset:24576
	ds_read_b64_tr_b16 v[114:115], v192 offset:24576
	ds_read_b64_tr_b16 v[116:117], v173 offset:24576
	ds_read_b64_tr_b16 v[118:119], v193 offset:24576
	ds_read_b64_tr_b16 v[120:121], v174 offset:24576
	ds_read_b64_tr_b16 v[122:123], v194 offset:24576
	ds_read_b64_tr_b16 v[124:125], v175 offset:24576
	ds_read_b64_tr_b16 v[126:127], v197 offset:24576
	s_waitcnt lgkmcnt(6)
	v_mfma_f32_32x32x16_bf16 v[0:15], v[88:91], v[112:115], v[0:15]
	ds_read_b64_tr_b16 v[112:113], v172 offset:28672
	ds_read_b64_tr_b16 v[114:115], v192 offset:28672
	s_waitcnt lgkmcnt(6)
	v_mfma_f32_32x32x16_bf16 v[16:31], v[88:91], v[116:119], v[16:31]
	ds_read_b64_tr_b16 v[116:117], v173 offset:28672
	ds_read_b64_tr_b16 v[118:119], v193 offset:28672
	s_waitcnt lgkmcnt(6)
	v_mfma_f32_32x32x16_bf16 v[32:47], v[88:91], v[120:123], v[32:47]
	ds_read_b64_tr_b16 v[120:121], v174 offset:28672
	ds_read_b64_tr_b16 v[122:123], v194 offset:28672
	s_waitcnt lgkmcnt(6)
	v_mfma_f32_32x32x16_bf16 v[48:63], v[88:91], v[124:127], v[48:63]
	ds_read_b64_tr_b16 v[124:125], v175 offset:28672
	ds_read_b64_tr_b16 v[126:127], v197 offset:28672
	s_waitcnt lgkmcnt(6)
	v_mfma_f32_32x32x16_bf16 v[0:15], v[92:95], v[112:115], v[0:15]
	s_waitcnt lgkmcnt(4)
	v_mfma_f32_32x32x16_bf16 v[16:31], v[92:95], v[116:119], v[16:31]
	s_waitcnt lgkmcnt(2)
	v_mfma_f32_32x32x16_bf16 v[32:47], v[92:95], v[120:123], v[32:47]
	s_waitcnt lgkmcnt(0)
	v_mfma_f32_32x32x16_bf16 v[48:63], v[92:95], v[124:127], v[48:63]

.Lpa_w1_2:
	s_barrier
	s_cmp_lt_i32 s54, s29
	s_cbranch_scc0 .Lpa_nodma_2
	s_add_i32 m0, s38, 0xc000
	s_nop 0
	global_load_lds_dwordx4 v166, s[58:59]
	s_add_i32 m0, s57, 0xc000
	s_nop 0
	global_load_lds_dwordx4 v170, s[58:59]
	s_add_u32 s58, s58, 0x10000
	s_addc_u32 s59, s59, 0
	s_cmp_gt_i32 s54, s53
	s_cbranch_scc1 .Lpa_nodma_2
	s_add_i32 m0, s38, 0x4000
	s_nop 0
	global_load_lds_dwordx4 v166, s[24:25]
	s_add_i32 m0, s57, 0x4000
	s_nop 0
	global_load_lds_dwordx4 v170, s[24:25]
	s_add_u32 s24, s24, 0x10000
	s_addc_u32 s25, s25, 0
.Lpa_nodma_2:
	s_cmp_gt_i32 s54, vcc_lo
	s_cbranch_scc1 .Lpa_next_2
	ds_read_b128 v[96:99], v191 offset:32768
	ds_read_b128 v[100:103], v190 offset:32768
	ds_read_b128 v[104:107], v189 offset:32768
	ds_read_b128 v[108:111], v188 offset:32768
	ds_read_b64_tr_b16 v[112:113], v172 offset:24576
	ds_read_b64_tr_b16 v[114:115], v192 offset:24576
	ds_read_b64_tr_b16 v[116:117], v173 offset:24576
	ds_read_b64_tr_b16 v[118:119], v193 offset:24576
	ds_read_b64_tr_b16 v[120:121], v174 offset:24576
	ds_read_b64_tr_b16 v[122:123], v194 offset:24576
	ds_read_b64_tr_b16 v[124:125], v175 offset:24576
	ds_read_b64_tr_b16 v[126:127], v197 offset:24576
	s_waitcnt lgkmcnt(11)
	v_mfma_f32_32x32x16_bf16 v[64:79], v[96:99], v[156:159], 0
	s_waitcnt lgkmcnt(10)
	v_mfma_f32_32x32x16_bf16 v[64:79], v[100:103], v[152:155], v[64:79]
	s_waitcnt lgkmcnt(9)
	v_mfma_f32_32x32x16_bf16 v[64:79], v[104:107], v[148:151], v[64:79]
	s_waitcnt lgkmcnt(8)
	v_mfma_f32_32x32x16_bf16 v[64:79], v[108:111], v[144:147], v[64:79]
	s_waitcnt lgkmcnt(6)
	v_mfma_f32_32x32x16_bf16 v[0:15], v[88:91], v[112:115], v[0:15]
	ds_read_b64_tr_b16 v[112:113], v172 offset:28672
	ds_read_b64_tr_b16 v[114:115], v192 offset:28672
	s_waitcnt lgkmcnt(6)
	v_mfma_f32_32x32x16_bf16 v[16:31], v[88:91], v[116:119], v[16:31]
	ds_read_b64_tr_b16 v[116:117], v173 offset:28672
	ds_read_b64_tr_b16 v[118:119], v193 offset:28672
	s_waitcnt lgkmcnt(6)
	v_mfma_f32_32x32x16_bf16 v[32:47], v[88:91], v[120:123], v[32:47]
	ds_read_b64_tr_b16 v[120:121], v174 offset:28672
	ds_read_b64_tr_b16 v[122:123], v194 offset:28672
	v_exp_f32_e32 v64, v64
	v_exp_f32_e32 v65, v65
	v_exp_f32_e32 v66, v66
	v_exp_f32_e32 v67, v67
	v_pk_add_f32 v[198:199], v[198:199], v[64:65]
	v_pk_add_f32 v[200:201], v[200:201], v[66:67]
	s_waitcnt lgkmcnt(6)
	v_mfma_f32_32x32x16_bf16 v[48:63], v[88:91], v[124:127], v[48:63]
	ds_read_b64_tr_b16 v[124:125], v175 offset:28672
	ds_read_b64_tr_b16 v[126:127], v197 offset:28672
	v_exp_f32_e32 v68, v68
	v_exp_f32_e32 v69, v69
	v_exp_f32_e32 v70, v70
	v_exp_f32_e32 v71, v71
	v_pk_add_f32 v[198:199], v[198:199], v[68:69]
	v_pk_add_f32 v[200:201], v[200:201], v[70:71]
	s_waitcnt lgkmcnt(6)
	v_mfma_f32_32x32x16_bf16 v[0:15], v[92:95], v[112:115], v[0:15]
	v_exp_f32_e32 v72, v72
	v_exp_f32_e32 v73, v73
	v_exp_f32_e32 v74, v74
	v_exp_f32_e32 v75, v75
	v_pk_add_f32 v[198:199], v[198:199], v[72:73]
	v_pk_add_f32 v[200:201], v[200:201], v[74:75]
	s_waitcnt lgkmcnt(4)
	v_mfma_f32_32x32x16_bf16 v[16:31], v[92:95], v[116:119], v[16:31]
	v_exp_f32_e32 v76, v76
	v_exp_f32_e32 v77, v77
	v_exp_f32_e32 v78, v78
	v_exp_f32_e32 v79, v79
	v_pk_add_f32 v[198:199], v[198:199], v[76:77]
	v_pk_add_f32 v[200:201], v[200:201], v[78:79]
	s_waitcnt lgkmcnt(2)
	v_mfma_f32_32x32x16_bf16 v[32:47], v[92:95], v[120:123], v[32:47]
	v_cvt_pk_bf16_f32 v80, v64, v65
	v_cvt_pk_bf16_f32 v81, v66, v67
	v_cvt_pk_bf16_f32 v82, v68, v69
	v_cvt_pk_bf16_f32 v83, v70, v71
	s_waitcnt lgkmcnt(0)
	v_mfma_f32_32x32x16_bf16 v[48:63], v[92:95], v[124:127], v[48:63]
	v_cvt_pk_bf16_f32 v84, v72, v73
	v_cvt_pk_bf16_f32 v85, v74, v75
	v_cvt_pk_bf16_f32 v86, v76, v77
	v_cvt_pk_bf16_f32 v87, v78, v79
.Lpa_h1_2:
	ds_read_b128 v[96:99], v191 offset:40960
	ds_read_b128 v[100:103], v190 offset:40960
	ds_read_b128 v[104:107], v189 offset:40960
	ds_read_b128 v[108:111], v188 offset:40960
	ds_read_b64_tr_b16 v[112:113], v172 offset:32768
	ds_read_b64_tr_b16 v[114:115], v192 offset:32768
	ds_read_b64_tr_b16 v[116:117], v173 offset:32768
	ds_read_b64_tr_b16 v[118:119], v193 offset:32768
	ds_read_b64_tr_b16 v[120:121], v174 offset:32768
	ds_read_b64_tr_b16 v[122:123], v194 offset:32768
	ds_read_b64_tr_b16 v[124:125], v175 offset:32768
	ds_read_b64_tr_b16 v[126:127], v197 offset:32768
	s_waitcnt lgkmcnt(11)
	v_mfma_f32_32x32x16_bf16 v[64:79], v[96:99], v[156:159], 0
	s_waitcnt lgkmcnt(10)
	v_mfma_f32_32x32x16_bf16 v[64:79], v[100:103], v[152:155], v[64:79]
	s_waitcnt lgkmcnt(9)
	v_mfma_f32_32x32x16_bf16 v[64:79], v[104:107], v[148:151], v[64:79]
	s_waitcnt lgkmcnt(8)
	v_mfma_f32_32x32x16_bf16 v[64:79], v[108:111], v[144:147], v[64:79]
	s_waitcnt lgkmcnt(6)
	v_mfma_f32_32x32x16_bf16 v[0:15], v[80:83], v[112:115], v[0:15]
	ds_read_b64_tr_b16 v[112:113], v172 offset:36864
	ds_read_b64_tr_b16 v[114:115], v192 offset:36864
	s_waitcnt lgkmcnt(6)
	v_mfma_f32_32x32x16_bf16 v[16:31], v[80:83], v[116:119], v[16:31]
	ds_read_b64_tr_b16 v[116:117], v173 offset:36864
	ds_read_b64_tr_b16 v[118:119], v193 offset:36864
	s_waitcnt lgkmcnt(6)
	v_mfma_f32_32x32x16_bf16 v[32:47], v[80:83], v[120:123], v[32:47]
	ds_read_b64_tr_b16 v[120:121], v174 offset:36864
	ds_read_b64_tr_b16 v[122:123], v194 offset:36864
	v_exp_f32_e32 v64, v64
	v_exp_f32_e32 v65, v65
	v_exp_f32_e32 v66, v66
	v_exp_f32_e32 v67, v67
	v_pk_add_f32 v[198:199], v[198:199], v[64:65]
	v_pk_add_f32 v[200:201], v[200:201], v[66:67]
	s_waitcnt lgkmcnt(6)
	v_mfma_f32_32x32x16_bf16 v[48:63], v[80:83], v[124:127], v[48:63]
	ds_read_b64_tr_b16 v[124:125], v175 offset:36864
	ds_read_b64_tr_b16 v[126:127], v197 offset:36864
	v_exp_f32_e32 v68, v68
	v_exp_f32_e32 v69, v69
	v_exp_f32_e32 v70, v70
	v_exp_f32_e32 v71, v71
	v_pk_add_f32 v[198:199], v[198:199], v[68:69]
	v_pk_add_f32 v[200:201], v[200:201], v[70:71]
	s_waitcnt lgkmcnt(6)
	v_mfma_f32_32x32x16_bf16 v[0:15], v[84:87], v[112:115], v[0:15]
	v_exp_f32_e32 v72, v72
	v_exp_f32_e32 v73, v73
	v_exp_f32_e32 v74, v74
	v_exp_f32_e32 v75, v75
	v_pk_add_f32 v[198:199], v[198:199], v[72:73]
	v_pk_add_f32 v[200:201], v[200:201], v[74:75]
	s_waitcnt lgkmcnt(4)
	v_mfma_f32_32x32x16_bf16 v[16:31], v[84:87], v[116:119], v[16:31]
	v_exp_f32_e32 v76, v76
	v_exp_f32_e32 v77, v77
	v_exp_f32_e32 v78, v78
	v_exp_f32_e32 v79, v79
	v_pk_add_f32 v[198:199], v[198:199], v[76:77]
	v_pk_add_f32 v[200:201], v[200:201], v[78:79]
	s_waitcnt lgkmcnt(2)
	v_mfma_f32_32x32x16_bf16 v[32:47], v[84:87], v[120:123], v[32:47]
	v_cvt_pk_bf16_f32 v88, v64, v65
	v_cvt_pk_bf16_f32 v89, v66, v67
	v_cvt_pk_bf16_f32 v90, v68, v69
	v_cvt_pk_bf16_f32 v91, v70, v71
	s_waitcnt lgkmcnt(0)
	v_mfma_f32_32x32x16_bf16 v[48:63], v[84:87], v[124:127], v[48:63]
	v_cvt_pk_bf16_f32 v92, v72, v73
	v_cvt_pk_bf16_f32 v93, v74, v75
	v_cvt_pk_bf16_f32 v94, v76, v77
	v_cvt_pk_bf16_f32 v95, v78, v79
	s_cmp_lt_i32 s54, vcc_lo
	s_cbranch_scc1 .Lpa_next_2
	s_nop 1
	ds_read_b64_tr_b16 v[112:113], v172 offset:40960
	ds_read_b64_tr_b16 v[114:115], v192 offset:40960
	ds_read_b64_tr_b16 v[116:117], v173 offset:40960
	ds_read_b64_tr_b16 v[118:119], v193 offset:40960
	ds_read_b64_tr_b16 v[120:121], v174 offset:40960
	ds_read_b64_tr_b16 v[122:123], v194 offset:40960
	ds_read_b64_tr_b16 v[124:125], v175 offset:40960
	ds_read_b64_tr_b16 v[126:127], v197 offset:40960
	s_waitcnt lgkmcnt(6)
	v_mfma_f32_32x32x16_bf16 v[0:15], v[88:91], v[112:115], v[0:15]
	ds_read_b64_tr_b16 v[112:113], v172 offset:45056
	ds_read_b64_tr_b16 v[114:115], v192 offset:45056
	s_waitcnt lgkmcnt(6)
	v_mfma_f32_32x32x16_bf16 v[16:31], v[88:91], v[116:119], v[16:31]
	ds_read_b64_tr_b16 v[116:117], v173 offset:45056
	ds_read_b64_tr_b16 v[118:119], v193 offset:45056
	s_waitcnt lgkmcnt(6)
	v_mfma_f32_32x32x16_bf16 v[32:47], v[88:91], v[120:123], v[32:47]
	ds_read_b64_tr_b16 v[120:121], v174 offset:45056
	ds_read_b64_tr_b16 v[122:123], v194 offset:45056
	s_waitcnt lgkmcnt(6)
	v_mfma_f32_32x32x16_bf16 v[48:63], v[88:91], v[124:127], v[48:63]
	ds_read_b64_tr_b16 v[124:125], v175 offset:45056
	ds_read_b64_tr_b16 v[126:127], v197 offset:45056
	s_waitcnt lgkmcnt(6)
	v_mfma_f32_32x32x16_bf16 v[0:15], v[92:95], v[112:115], v[0:15]
	s_waitcnt lgkmcnt(4)
	v_mfma_f32_32x32x16_bf16 v[16:31], v[92:95], v[116:119], v[16:31]
	s_waitcnt lgkmcnt(2)
	v_mfma_f32_32x32x16_bf16 v[32:47], v[92:95], v[120:123], v[32:47]
	s_waitcnt lgkmcnt(0)
	v_mfma_f32_32x32x16_bf16 v[48:63], v[92:95], v[124:127], v[48:63]
.Lpa_next_2:
	s_cmp_lt_i32 s54, s29
	s_cbranch_scc1 .Lpa_step0
.Lpa_done:
	v_pk_add_f32 v[198:199], v[198:199], v[200:201]
	s_nop 1
	v_add_f32_e32 v198, v198, v199
	ds_bpermute_b32 v200, v169, v198
	s_waitcnt lgkmcnt(0)
	v_add_f32_e32 v198, v198, v200
	v_rcp_f32_e32 v167, v198
	s_barrier
	v_mov_b32_e32 v198, 0
	v_mov_b32_e32 v199, 0
	v_mov_b32_e32 v200, 0
	v_mov_b32_e32 v201, 0
	v_mov_b32_e32 v202, 0
	v_mov_b32_e32 v203, 0
	v_mov_b32_e32 v204, 0
	v_mov_b32_e32 v205, 0
	v_mov_b32_e32 v206, 0
	v_mov_b32_e32 v207, 0
	v_mov_b32_e32 v208, 0
	v_mov_b32_e32 v209, 0
	v_mov_b32_e32 v210, 0
	v_mov_b32_e32 v211, 0
	v_mov_b32_e32 v212, 0
	v_mov_b32_e32 v213, 0
	v_mov_b32_e32 v214, 0
	v_mov_b32_e32 v215, 0
	v_mov_b32_e32 v216, 0
	v_mov_b32_e32 v217, 0
	v_mov_b32_e32 v218, 0
	v_mov_b32_e32 v219, 0
	v_mov_b32_e32 v220, 0
	v_mov_b32_e32 v221, 0
	v_mov_b32_e32 v222, 0
	v_mov_b32_e32 v223, 0
	v_mov_b32_e32 v224, 0
	v_mov_b32_e32 v225, 0
	v_mov_b32_e32 v226, 0
	v_mov_b32_e32 v227, 0
	v_mov_b32_e32 v228, 0
	v_mov_b32_e32 v229, 0
	v_mov_b32_e32 v230, 0
	v_mov_b32_e32 v231, 0
	v_mov_b32_e32 v232, 0
	v_mov_b32_e32 v233, 0
	v_mov_b32_e32 v234, 0
	v_mov_b32_e32 v235, 0
	v_mov_b32_e32 v236, 0
	v_mov_b32_e32 v237, 0
	v_mov_b32_e32 v238, 0
	v_mov_b32_e32 v239, 0
	v_mov_b32_e32 v240, 0
	v_mov_b32_e32 v241, 0
	v_mov_b32_e32 v242, 0
	v_mov_b32_e32 v243, 0
	v_mov_b32_e32 v244, 0
	v_mov_b32_e32 v245, 0
	v_mov_b32_e32 v144, 0
	v_mov_b32_e32 v145, 0
	v_mov_b32_e32 v146, 0
	v_mov_b32_e32 v147, 0
	v_mov_b32_e32 v148, 0
	v_mov_b32_e32 v149, 0
	v_mov_b32_e32 v150, 0
	v_mov_b32_e32 v151, 0
	v_mov_b32_e32 v152, 0
	v_mov_b32_e32 v153, 0
	v_mov_b32_e32 v154, 0
	v_mov_b32_e32 v155, 0
	v_mov_b32_e32 v156, 0
	v_mov_b32_e32 v157, 0
	v_mov_b32_e32 v158, 0
	v_mov_b32_e32 v159, 0
	s_mov_b64 s[24:25], s[22:23]
	s_add_u32 s58, s22, 0x2000000
	s_addc_u32 s59, s23, 0
	s_mov_b32 m0, s38
	s_nop 0
	global_load_lds_dwordx4 v166, s[24:25]
	s_mov_b32 m0, s57
	s_nop 0
	global_load_lds_dwordx4 v170, s[24:25]
	s_add_u32 s24, s24, 0x10000
	s_addc_u32 s25, s25, 0
	s_add_i32 m0, s38, 0xc000
	s_nop 0
	global_load_lds_dwordx4 v166, s[58:59]
	s_add_i32 m0, s57, 0xc000
	s_nop 0
	global_load_lds_dwordx4 v170, s[58:59]
	s_add_u32 s58, s58, 0x10000
	s_addc_u32 s59, s59, 0
	s_add_i32 m0, s38, 0x4000
	s_nop 0
	global_load_lds_dwordx4 v166, s[24:25]
	s_add_i32 m0, s57, 0x4000
	s_nop 0
	global_load_lds_dwordx4 v170, s[24:25]
	s_add_u32 s24, s24, 0x10000
	s_addc_u32 s25, s25, 0
	s_mov_b32 s54, 0
	v_mov_b32_e32 v188, 0
	v_mov_b32_e32 v189, 0
	v_mov_b32_e32 v190, 0
	v_mov_b32_e32 v191, 0

.Lpb_nodma_0:
	s_cmp_gt_i32 s54, vcc_lo
	s_cbranch_scc1 .Lpb_next_0
	s_cmp_eq_u32 s54, 1
	s_cbranch_scc0 .Lpb_pend_0
	ds_read_b128 v[96:99], v187 offset:0
	ds_read_b128 v[100:103], v186 offset:0
	ds_read_b128 v[104:107], v185 offset:0
	ds_read_b128 v[108:111], v184 offset:0
	s_waitcnt lgkmcnt(3)
	v_mfma_f32_32x32x16_bf16 v[64:79], v[96:99], v[140:143], 0
	s_waitcnt lgkmcnt(2)
	v_mfma_f32_32x32x16_bf16 v[64:79], v[100:103], v[136:139], v[64:79]
	s_waitcnt lgkmcnt(1)
	v_mfma_f32_32x32x16_bf16 v[64:79], v[104:107], v[132:135], v[64:79]
	s_waitcnt lgkmcnt(0)
	v_mfma_f32_32x32x16_bf16 v[64:79], v[108:111], v[128:131], v[64:79]
	s_nop 11
	v_exp_f32_e32 v64, v64
	v_exp_f32_e32 v65, v65
	v_exp_f32_e32 v66, v66
	v_exp_f32_e32 v67, v67
	v_pk_add_f32 v[188:189], v[188:189], v[64:65]
	v_pk_add_f32 v[190:191], v[190:191], v[66:67]
	v_exp_f32_e32 v68, v68
	v_exp_f32_e32 v69, v69
	v_exp_f32_e32 v70, v70
	v_exp_f32_e32 v71, v71
	v_pk_add_f32 v[188:189], v[188:189], v[68:69]
	v_pk_add_f32 v[190:191], v[190:191], v[70:71]
	v_exp_f32_e32 v72, v72
	v_exp_f32_e32 v73, v73
	v_exp_f32_e32 v74, v74
	v_exp_f32_e32 v75, v75
	v_pk_add_f32 v[188:189], v[188:189], v[72:73]
	v_pk_add_f32 v[190:191], v[190:191], v[74:75]
	v_exp_f32_e32 v76, v76
	v_exp_f32_e32 v77, v77
	v_exp_f32_e32 v78, v78
	v_exp_f32_e32 v79, v79
	v_pk_add_f32 v[188:189], v[188:189], v[76:77]
	v_pk_add_f32 v[190:191], v[190:191], v[78:79]
	v_cvt_pk_bf16_f32 v80, v64, v65
	v_cvt_pk_bf16_f32 v81, v66, v67
	v_cvt_pk_bf16_f32 v82, v68, v69
	v_cvt_pk_bf16_f32 v83, v70, v71
	v_cvt_pk_bf16_f32 v84, v72, v73
	v_cvt_pk_bf16_f32 v85, v74, v75
	v_cvt_pk_bf16_f32 v86, v76, v77
	v_cvt_pk_bf16_f32 v87, v78, v79
	s_branch .Lpb_h1_0
.Lpb_pend_0:
	ds_read_b128 v[96:99], v187 offset:0
	ds_read_b128 v[100:103], v186 offset:0
	ds_read_b128 v[104:107], v185 offset:0
	ds_read_b128 v[108:111], v184 offset:0
	ds_read_b64_tr_b16 v[112:113], v172 offset:40960
	ds_read_b64_tr_b16 v[114:115], v192 offset:40960
	ds_read_b64_tr_b16 v[116:117], v173 offset:40960
	ds_read_b64_tr_b16 v[118:119], v193 offset:40960
	ds_read_b64_tr_b16 v[120:121], v174 offset:40960
	ds_read_b64_tr_b16 v[122:123], v194 offset:40960
	ds_read_b64_tr_b16 v[124:125], v175 offset:40960
	ds_read_b64_tr_b16 v[126:127], v197 offset:40960
	s_waitcnt lgkmcnt(11)
	v_mfma_f32_32x32x16_bf16 v[64:79], v[96:99], v[140:143], 0
	s_waitcnt lgkmcnt(10)
	v_mfma_f32_32x32x16_bf16 v[64:79], v[100:103], v[136:139], v[64:79]
	s_waitcnt lgkmcnt(9)
	v_mfma_f32_32x32x16_bf16 v[64:79], v[104:107], v[132:135], v[64:79]
	s_waitcnt lgkmcnt(8)
	v_mfma_f32_32x32x16_bf16 v[64:79], v[108:111], v[128:131], v[64:79]
	s_waitcnt lgkmcnt(6)
	v_mfma_f32_32x32x16_bf16 v[198:213], v[88:91], v[112:115], v[198:213]
	ds_read_b64_tr_b16 v[112:113], v172 offset:45056
	ds_read_b64_tr_b16 v[114:115], v192 offset:45056
	s_waitcnt lgkmcnt(6)
	v_mfma_f32_32x32x16_bf16 v[214:229], v[88:91], v[116:119], v[214:229]
	ds_read_b64_tr_b16 v[116:117], v173 offset:45056
	ds_read_b64_tr_b16 v[118:119], v193 offset:45056
	s_waitcnt lgkmcnt(6)
	v_mfma_f32_32x32x16_bf16 v[230:245], v[88:91], v[120:123], v[230:245]
	ds_read_b64_tr_b16 v[120:121], v174 offset:45056
	ds_read_b64_tr_b16 v[122:123], v194 offset:45056
	v_exp_f32_e32 v64, v64
	v_exp_f32_e32 v65, v65
	v_exp_f32_e32 v66, v66
	v_exp_f32_e32 v67, v67
	v_pk_add_f32 v[188:189], v[188:189], v[64:65]
	v_pk_add_f32 v[190:191], v[190:191], v[66:67]
	s_waitcnt lgkmcnt(6)
	v_mfma_f32_32x32x16_bf16 v[144:159], v[88:91], v[124:127], v[144:159]
	ds_read_b64_tr_b16 v[124:125], v175 offset:45056
	ds_read_b64_tr_b16 v[126:127], v197 offset:45056
	v_exp_f32_e32 v68, v68
	v_exp_f32_e32 v69, v69
	v_exp_f32_e32 v70, v70
	v_exp_f32_e32 v71, v71
	v_pk_add_f32 v[188:189], v[188:189], v[68:69]
	v_pk_add_f32 v[190:191], v[190:191], v[70:71]
	s_waitcnt lgkmcnt(6)
	v_mfma_f32_32x32x16_bf16 v[198:213], v[92:95], v[112:115], v[198:213]
	v_exp_f32_e32 v72, v72
	v_exp_f32_e32 v73, v73
	v_exp_f32_e32 v74, v74
	v_exp_f32_e32 v75, v75
	v_pk_add_f32 v[188:189], v[188:189], v[72:73]
	v_pk_add_f32 v[190:191], v[190:191], v[74:75]
	s_waitcnt lgkmcnt(4)
	v_mfma_f32_32x32x16_bf16 v[214:229], v[92:95], v[116:119], v[214:229]
	v_exp_f32_e32 v76, v76
	v_exp_f32_e32 v77, v77
	v_exp_f32_e32 v78, v78
	v_exp_f32_e32 v79, v79
	v_pk_add_f32 v[188:189], v[188:189], v[76:77]
	v_pk_add_f32 v[190:191], v[190:191], v[78:79]
	s_waitcnt lgkmcnt(2)
	v_mfma_f32_32x32x16_bf16 v[230:245], v[92:95], v[120:123], v[230:245]
	v_cvt_pk_bf16_f32 v80, v64, v65
	v_cvt_pk_bf16_f32 v81, v66, v67
	v_cvt_pk_bf16_f32 v82, v68, v69
	v_cvt_pk_bf16_f32 v83, v70, v71
	s_waitcnt lgkmcnt(0)
	v_mfma_f32_32x32x16_bf16 v[144:159], v[92:95], v[124:127], v[144:159]
	v_cvt_pk_bf16_f32 v84, v72, v73
	v_cvt_pk_bf16_f32 v85, v74, v75
	v_cvt_pk_bf16_f32 v86, v76, v77
	v_cvt_pk_bf16_f32 v87, v78, v79
.Lpb_h1_0:
	ds_read_b128 v[96:99], v187 offset:8192
	ds_read_b128 v[100:103], v186 offset:8192
	ds_read_b128 v[104:107], v185 offset:8192
	ds_read_b128 v[108:111], v184 offset:8192
	ds_read_b64_tr_b16 v[112:113], v172 offset:0
	ds_read_b64_tr_b16 v[114:115], v192 offset:0
	ds_read_b64_tr_b16 v[116:117], v173 offset:0
	ds_read_b64_tr_b16 v[118:119], v193 offset:0
	ds_read_b64_tr_b16 v[120:121], v174 offset:0
	ds_read_b64_tr_b16 v[122:123], v194 offset:0
	ds_read_b64_tr_b16 v[124:125], v175 offset:0
	ds_read_b64_tr_b16 v[126:127], v197 offset:0
	s_waitcnt lgkmcnt(11)
	v_mfma_f32_32x32x16_bf16 v[64:79], v[96:99], v[140:143], 0
	s_waitcnt lgkmcnt(10)
	v_mfma_f32_32x32x16_bf16 v[64:79], v[100:103], v[136:139], v[64:79]
	s_waitcnt lgkmcnt(9)
	v_mfma_f32_32x32x16_bf16 v[64:79], v[104:107], v[132:135], v[64:79]
	s_waitcnt lgkmcnt(8)
	v_mfma_f32_32x32x16_bf16 v[64:79], v[108:111], v[128:131], v[64:79]
	s_waitcnt lgkmcnt(6)
	v_mfma_f32_32x32x16_bf16 v[198:213], v[80:83], v[112:115], v[198:213]
	ds_read_b64_tr_b16 v[112:113], v172 offset:4096
	ds_read_b64_tr_b16 v[114:115], v192 offset:4096
	s_waitcnt lgkmcnt(6)
	v_mfma_f32_32x32x16_bf16 v[214:229], v[80:83], v[116:119], v[214:229]
	ds_read_b64_tr_b16 v[116:117], v173 offset:4096
	ds_read_b64_tr_b16 v[118:119], v193 offset:4096
	s_waitcnt lgkmcnt(6)
	v_mfma_f32_32x32x16_bf16 v[230:245], v[80:83], v[120:123], v[230:245]
	ds_read_b64_tr_b16 v[120:121], v174 offset:4096
	ds_read_b64_tr_b16 v[122:123], v194 offset:4096
	v_exp_f32_e32 v64, v64
	v_exp_f32_e32 v65, v65
	v_exp_f32_e32 v66, v66
	v_exp_f32_e32 v67, v67
	v_pk_add_f32 v[188:189], v[188:189], v[64:65]
	v_pk_add_f32 v[190:191], v[190:191], v[66:67]
	s_waitcnt lgkmcnt(6)
	v_mfma_f32_32x32x16_bf16 v[144:159], v[80:83], v[124:127], v[144:159]
	ds_read_b64_tr_b16 v[124:125], v175 offset:4096
	ds_read_b64_tr_b16 v[126:127], v197 offset:4096
	v_exp_f32_e32 v68, v68
	v_exp_f32_e32 v69, v69
	v_exp_f32_e32 v70, v70
	v_exp_f32_e32 v71, v71
	v_pk_add_f32 v[188:189], v[188:189], v[68:69]
	v_pk_add_f32 v[190:191], v[190:191], v[70:71]
	s_waitcnt lgkmcnt(6)
	v_mfma_f32_32x32x16_bf16 v[198:213], v[84:87], v[112:115], v[198:213]
	v_exp_f32_e32 v72, v72
	v_exp_f32_e32 v73, v73
	v_exp_f32_e32 v74, v74
	v_exp_f32_e32 v75, v75
	v_pk_add_f32 v[188:189], v[188:189], v[72:73]
	v_pk_add_f32 v[190:191], v[190:191], v[74:75]
	s_waitcnt lgkmcnt(4)
	v_mfma_f32_32x32x16_bf16 v[214:229], v[84:87], v[116:119], v[214:229]
	v_exp_f32_e32 v76, v76
	v_exp_f32_e32 v77, v77
	v_exp_f32_e32 v78, v78
	v_exp_f32_e32 v79, v79
	v_pk_add_f32 v[188:189], v[188:189], v[76:77]
	v_pk_add_f32 v[190:191], v[190:191], v[78:79]
	s_waitcnt lgkmcnt(2)
	v_mfma_f32_32x32x16_bf16 v[230:245], v[84:87], v[120:123], v[230:245]
	v_cvt_pk_bf16_f32 v88, v64, v65
	v_cvt_pk_bf16_f32 v89, v66, v67
	v_cvt_pk_bf16_f32 v90, v68, v69
	v_cvt_pk_bf16_f32 v91, v70, v71
	s_waitcnt lgkmcnt(0)
	v_mfma_f32_32x32x16_bf16 v[144:159], v[84:87], v[124:127], v[144:159]
	v_cvt_pk_bf16_f32 v92, v72, v73
	v_cvt_pk_bf16_f32 v93, v74, v75
	v_cvt_pk_bf16_f32 v94, v76, v77
	v_cvt_pk_bf16_f32 v95, v78, v79
	s_cmp_lt_i32 s54, vcc_lo
	s_cbranch_scc1 .Lpb_next_0
	s_nop 1
	ds_read_b64_tr_b16 v[112:113], v172 offset:8192
	ds_read_b64_tr_b16 v[114:115], v192 offset:8192
	ds_read_b64_tr_b16 v[116:117], v173 offset:8192
	ds_read_b64_tr_b16 v[118:119], v193 offset:8192
	ds_read_b64_tr_b16 v[120:121], v174 offset:8192
	ds_read_b64_tr_b16 v[122:123], v194 offset:8192
	ds_read_b64_tr_b16 v[124:125], v175 offset:8192
	ds_read_b64_tr_b16 v[126:127], v197 offset:8192
	s_waitcnt lgkmcnt(6)
	v_mfma_f32_32x32x16_bf16 v[198:213], v[88:91], v[112:115], v[198:213]
	ds_read_b64_tr_b16 v[112:113], v172 offset:12288
	ds_read_b64_tr_b16 v[114:115], v192 offset:12288
	s_waitcnt lgkmcnt(6)
	v_mfma_f32_32x32x16_bf16 v[214:229], v[88:91], v[116:119], v[214:229]
	ds_read_b64_tr_b16 v[116:117], v173 offset:12288
	ds_read_b64_tr_b16 v[118:119], v193 offset:12288
	s_waitcnt lgkmcnt(6)
	v_mfma_f32_32x32x16_bf16 v[230:245], v[88:91], v[120:123], v[230:245]
	ds_read_b64_tr_b16 v[120:121], v174 offset:12288
	ds_read_b64_tr_b16 v[122:123], v194 offset:12288
	s_waitcnt lgkmcnt(6)
	v_mfma_f32_32x32x16_bf16 v[144:159], v[88:91], v[124:127], v[144:159]
	ds_read_b64_tr_b16 v[124:125], v175 offset:12288
	ds_read_b64_tr_b16 v[126:127], v197 offset:12288
	s_waitcnt lgkmcnt(6)
	v_mfma_f32_32x32x16_bf16 v[198:213], v[92:95], v[112:115], v[198:213]
	s_waitcnt lgkmcnt(4)
	v_mfma_f32_32x32x16_bf16 v[214:229], v[92:95], v[116:119], v[214:229]
	s_waitcnt lgkmcnt(2)
	v_mfma_f32_32x32x16_bf16 v[230:245], v[92:95], v[120:123], v[230:245]
	s_waitcnt lgkmcnt(0)
	v_mfma_f32_32x32x16_bf16 v[144:159], v[92:95], v[124:127], v[144:159]

.Lpb_nodma_1:
	s_cmp_gt_i32 s54, vcc_lo
	s_cbranch_scc1 .Lpb_next_1
	ds_read_b128 v[96:99], v187 offset:16384
	ds_read_b128 v[100:103], v186 offset:16384
	ds_read_b128 v[104:107], v185 offset:16384
	ds_read_b128 v[108:111], v184 offset:16384
	ds_read_b64_tr_b16 v[112:113], v172 offset:8192
	ds_read_b64_tr_b16 v[114:115], v192 offset:8192
	ds_read_b64_tr_b16 v[116:117], v173 offset:8192
	ds_read_b64_tr_b16 v[118:119], v193 offset:8192
	ds_read_b64_tr_b16 v[120:121], v174 offset:8192
	ds_read_b64_tr_b16 v[122:123], v194 offset:8192
	ds_read_b64_tr_b16 v[124:125], v175 offset:8192
	ds_read_b64_tr_b16 v[126:127], v197 offset:8192
	s_waitcnt lgkmcnt(11)
	v_mfma_f32_32x32x16_bf16 v[64:79], v[96:99], v[140:143], 0
	s_waitcnt lgkmcnt(10)
	v_mfma_f32_32x32x16_bf16 v[64:79], v[100:103], v[136:139], v[64:79]
	s_waitcnt lgkmcnt(9)
	v_mfma_f32_32x32x16_bf16 v[64:79], v[104:107], v[132:135], v[64:79]
	s_waitcnt lgkmcnt(8)
	v_mfma_f32_32x32x16_bf16 v[64:79], v[108:111], v[128:131], v[64:79]
	s_waitcnt lgkmcnt(6)
	v_mfma_f32_32x32x16_bf16 v[198:213], v[88:91], v[112:115], v[198:213]
	ds_read_b64_tr_b16 v[112:113], v172 offset:12288
	ds_read_b64_tr_b16 v[114:115], v192 offset:12288
	s_waitcnt lgkmcnt(6)
	v_mfma_f32_32x32x16_bf16 v[214:229], v[88:91], v[116:119], v[214:229]
	ds_read_b64_tr_b16 v[116:117], v173 offset:12288
	ds_read_b64_tr_b16 v[118:119], v193 offset:12288
	s_waitcnt lgkmcnt(6)
	v_mfma_f32_32x32x16_bf16 v[230:245], v[88:91], v[120:123], v[230:245]
	ds_read_b64_tr_b16 v[120:121], v174 offset:12288
	ds_read_b64_tr_b16 v[122:123], v194 offset:12288
	v_exp_f32_e32 v64, v64
	v_exp_f32_e32 v65, v65
	v_exp_f32_e32 v66, v66
	v_exp_f32_e32 v67, v67
	v_pk_add_f32 v[188:189], v[188:189], v[64:65]
	v_pk_add_f32 v[190:191], v[190:191], v[66:67]
	s_waitcnt lgkmcnt(6)
	v_mfma_f32_32x32x16_bf16 v[144:159], v[88:91], v[124:127], v[144:159]
	ds_read_b64_tr_b16 v[124:125], v175 offset:12288
	ds_read_b64_tr_b16 v[126:127], v197 offset:12288
	v_exp_f32_e32 v68, v68
	v_exp_f32_e32 v69, v69
	v_exp_f32_e32 v70, v70
	v_exp_f32_e32 v71, v71
	v_pk_add_f32 v[188:189], v[188:189], v[68:69]
	v_pk_add_f32 v[190:191], v[190:191], v[70:71]
	s_waitcnt lgkmcnt(6)
	v_mfma_f32_32x32x16_bf16 v[198:213], v[92:95], v[112:115], v[198:213]
	v_exp_f32_e32 v72, v72
	v_exp_f32_e32 v73, v73
	v_exp_f32_e32 v74, v74
	v_exp_f32_e32 v75, v75
	v_pk_add_f32 v[188:189], v[188:189], v[72:73]
	v_pk_add_f32 v[190:191], v[190:191], v[74:75]
	s_waitcnt lgkmcnt(4)
	v_mfma_f32_32x32x16_bf16 v[214:229], v[92:95], v[116:119], v[214:229]
	v_exp_f32_e32 v76, v76
	v_exp_f32_e32 v77, v77
	v_exp_f32_e32 v78, v78
	v_exp_f32_e32 v79, v79
	v_pk_add_f32 v[188:189], v[188:189], v[76:77]
	v_pk_add_f32 v[190:191], v[190:191], v[78:79]
	s_waitcnt lgkmcnt(2)
	v_mfma_f32_32x32x16_bf16 v[230:245], v[92:95], v[120:123], v[230:245]
	v_cvt_pk_bf16_f32 v80, v64, v65
	v_cvt_pk_bf16_f32 v81, v66, v67
	v_cvt_pk_bf16_f32 v82, v68, v69
	v_cvt_pk_bf16_f32 v83, v70, v71
	s_waitcnt lgkmcnt(0)
	v_mfma_f32_32x32x16_bf16 v[144:159], v[92:95], v[124:127], v[144:159]
	v_cvt_pk_bf16_f32 v84, v72, v73
	v_cvt_pk_bf16_f32 v85, v74, v75
	v_cvt_pk_bf16_f32 v86, v76, v77
	v_cvt_pk_bf16_f32 v87, v78, v79
.Lpb_h1_1:
	ds_read_b128 v[96:99], v187 offset:24576
	ds_read_b128 v[100:103], v186 offset:24576
	ds_read_b128 v[104:107], v185 offset:24576
	ds_read_b128 v[108:111], v184 offset:24576
	ds_read_b64_tr_b16 v[112:113], v172 offset:16384
	ds_read_b64_tr_b16 v[114:115], v192 offset:16384
	ds_read_b64_tr_b16 v[116:117], v173 offset:16384
	ds_read_b64_tr_b16 v[118:119], v193 offset:16384
	ds_read_b64_tr_b16 v[120:121], v174 offset:16384
	ds_read_b64_tr_b16 v[122:123], v194 offset:16384
	ds_read_b64_tr_b16 v[124:125], v175 offset:16384
	ds_read_b64_tr_b16 v[126:127], v197 offset:16384
	s_waitcnt lgkmcnt(11)
	v_mfma_f32_32x32x16_bf16 v[64:79], v[96:99], v[140:143], 0
	s_waitcnt lgkmcnt(10)
	v_mfma_f32_32x32x16_bf16 v[64:79], v[100:103], v[136:139], v[64:79]
	s_waitcnt lgkmcnt(9)
	v_mfma_f32_32x32x16_bf16 v[64:79], v[104:107], v[132:135], v[64:79]
	s_waitcnt lgkmcnt(8)
	v_mfma_f32_32x32x16_bf16 v[64:79], v[108:111], v[128:131], v[64:79]
	s_waitcnt lgkmcnt(6)
	v_mfma_f32_32x32x16_bf16 v[198:213], v[80:83], v[112:115], v[198:213]
	ds_read_b64_tr_b16 v[112:113], v172 offset:20480
	ds_read_b64_tr_b16 v[114:115], v192 offset:20480
	s_waitcnt lgkmcnt(6)
	v_mfma_f32_32x32x16_bf16 v[214:229], v[80:83], v[116:119], v[214:229]
	ds_read_b64_tr_b16 v[116:117], v173 offset:20480
	ds_read_b64_tr_b16 v[118:119], v193 offset:20480
	s_waitcnt lgkmcnt(6)
	v_mfma_f32_32x32x16_bf16 v[230:245], v[80:83], v[120:123], v[230:245]
	ds_read_b64_tr_b16 v[120:121], v174 offset:20480
	ds_read_b64_tr_b16 v[122:123], v194 offset:20480
	v_exp_f32_e32 v64, v64
	v_exp_f32_e32 v65, v65
	v_exp_f32_e32 v66, v66
	v_exp_f32_e32 v67, v67
	v_pk_add_f32 v[188:189], v[188:189], v[64:65]
	v_pk_add_f32 v[190:191], v[190:191], v[66:67]
	s_waitcnt lgkmcnt(6)
	v_mfma_f32_32x32x16_bf16 v[144:159], v[80:83], v[124:127], v[144:159]
	ds_read_b64_tr_b16 v[124:125], v175 offset:20480
	ds_read_b64_tr_b16 v[126:127], v197 offset:20480
	v_exp_f32_e32 v68, v68
	v_exp_f32_e32 v69, v69
	v_exp_f32_e32 v70, v70
	v_exp_f32_e32 v71, v71
	v_pk_add_f32 v[188:189], v[188:189], v[68:69]
	v_pk_add_f32 v[190:191], v[190:191], v[70:71]
	s_waitcnt lgkmcnt(6)
	v_mfma_f32_32x32x16_bf16 v[198:213], v[84:87], v[112:115], v[198:213]
	v_exp_f32_e32 v72, v72
	v_exp_f32_e32 v73, v73
	v_exp_f32_e32 v74, v74
	v_exp_f32_e32 v75, v75
	v_pk_add_f32 v[188:189], v[188:189], v[72:73]
	v_pk_add_f32 v[190:191], v[190:191], v[74:75]
	s_waitcnt lgkmcnt(4)
	v_mfma_f32_32x32x16_bf16 v[214:229], v[84:87], v[116:119], v[214:229]
	v_exp_f32_e32 v76, v76
	v_exp_f32_e32 v77, v77
	v_exp_f32_e32 v78, v78
	v_exp_f32_e32 v79, v79
	v_pk_add_f32 v[188:189], v[188:189], v[76:77]
	v_pk_add_f32 v[190:191], v[190:191], v[78:79]
	s_waitcnt lgkmcnt(2)
	v_mfma_f32_32x32x16_bf16 v[230:245], v[84:87], v[120:123], v[230:245]
	v_cvt_pk_bf16_f32 v88, v64, v65
	v_cvt_pk_bf16_f32 v89, v66, v67
	v_cvt_pk_bf16_f32 v90, v68, v69
	v_cvt_pk_bf16_f32 v91, v70, v71
	s_waitcnt lgkmcnt(0)
	v_mfma_f32_32x32x16_bf16 v[144:159], v[84:87], v[124:127], v[144:159]
	v_cvt_pk_bf16_f32 v92, v72, v73
	v_cvt_pk_bf16_f32 v93, v74, v75
	v_cvt_pk_bf16_f32 v94, v76, v77
	v_cvt_pk_bf16_f32 v95, v78, v79
	s_cmp_lt_i32 s54, vcc_lo
	s_cbranch_scc1 .Lpb_next_1
	s_nop 1
	ds_read_b64_tr_b16 v[112:113], v172 offset:24576
	ds_read_b64_tr_b16 v[114:115], v192 offset:24576
	ds_read_b64_tr_b16 v[116:117], v173 offset:24576
	ds_read_b64_tr_b16 v[118:119], v193 offset:24576
	ds_read_b64_tr_b16 v[120:121], v174 offset:24576
	ds_read_b64_tr_b16 v[122:123], v194 offset:24576
	ds_read_b64_tr_b16 v[124:125], v175 offset:24576
	ds_read_b64_tr_b16 v[126:127], v197 offset:24576
	s_waitcnt lgkmcnt(6)
	v_mfma_f32_32x32x16_bf16 v[198:213], v[88:91], v[112:115], v[198:213]
	ds_read_b64_tr_b16 v[112:113], v172 offset:28672
	ds_read_b64_tr_b16 v[114:115], v192 offset:28672
	s_waitcnt lgkmcnt(6)
	v_mfma_f32_32x32x16_bf16 v[214:229], v[88:91], v[116:119], v[214:229]
	ds_read_b64_tr_b16 v[116:117], v173 offset:28672
	ds_read_b64_tr_b16 v[118:119], v193 offset:28672
	s_waitcnt lgkmcnt(6)
	v_mfma_f32_32x32x16_bf16 v[230:245], v[88:91], v[120:123], v[230:245]
	ds_read_b64_tr_b16 v[120:121], v174 offset:28672
	ds_read_b64_tr_b16 v[122:123], v194 offset:28672
	s_waitcnt lgkmcnt(6)
	v_mfma_f32_32x32x16_bf16 v[144:159], v[88:91], v[124:127], v[144:159]
	ds_read_b64_tr_b16 v[124:125], v175 offset:28672
	ds_read_b64_tr_b16 v[126:127], v197 offset:28672
	s_waitcnt lgkmcnt(6)
	v_mfma_f32_32x32x16_bf16 v[198:213], v[92:95], v[112:115], v[198:213]
	s_waitcnt lgkmcnt(4)
	v_mfma_f32_32x32x16_bf16 v[214:229], v[92:95], v[116:119], v[214:229]
	s_waitcnt lgkmcnt(2)
	v_mfma_f32_32x32x16_bf16 v[230:245], v[92:95], v[120:123], v[230:245]
	s_waitcnt lgkmcnt(0)
	v_mfma_f32_32x32x16_bf16 v[144:159], v[92:95], v[124:127], v[144:159]

.Lpb_nodma_2:
	s_cmp_gt_i32 s54, vcc_lo
	s_cbranch_scc1 .Lpb_next_2
	ds_read_b128 v[96:99], v187 offset:32768
	ds_read_b128 v[100:103], v186 offset:32768
	ds_read_b128 v[104:107], v185 offset:32768
	ds_read_b128 v[108:111], v184 offset:32768
	ds_read_b64_tr_b16 v[112:113], v172 offset:24576
	ds_read_b64_tr_b16 v[114:115], v192 offset:24576
	ds_read_b64_tr_b16 v[116:117], v173 offset:24576
	ds_read_b64_tr_b16 v[118:119], v193 offset:24576
	ds_read_b64_tr_b16 v[120:121], v174 offset:24576
	ds_read_b64_tr_b16 v[122:123], v194 offset:24576
	ds_read_b64_tr_b16 v[124:125], v175 offset:24576
	ds_read_b64_tr_b16 v[126:127], v197 offset:24576
	s_waitcnt lgkmcnt(11)
	v_mfma_f32_32x32x16_bf16 v[64:79], v[96:99], v[140:143], 0
	s_waitcnt lgkmcnt(10)
	v_mfma_f32_32x32x16_bf16 v[64:79], v[100:103], v[136:139], v[64:79]
	s_waitcnt lgkmcnt(9)
	v_mfma_f32_32x32x16_bf16 v[64:79], v[104:107], v[132:135], v[64:79]
	s_waitcnt lgkmcnt(8)
	v_mfma_f32_32x32x16_bf16 v[64:79], v[108:111], v[128:131], v[64:79]
	s_waitcnt lgkmcnt(6)
	v_mfma_f32_32x32x16_bf16 v[198:213], v[88:91], v[112:115], v[198:213]
	ds_read_b64_tr_b16 v[112:113], v172 offset:28672
	ds_read_b64_tr_b16 v[114:115], v192 offset:28672
	s_waitcnt lgkmcnt(6)
	v_mfma_f32_32x32x16_bf16 v[214:229], v[88:91], v[116:119], v[214:229]
	ds_read_b64_tr_b16 v[116:117], v173 offset:28672
	ds_read_b64_tr_b16 v[118:119], v193 offset:28672
	s_waitcnt lgkmcnt(6)
	v_mfma_f32_32x32x16_bf16 v[230:245], v[88:91], v[120:123], v[230:245]
	ds_read_b64_tr_b16 v[120:121], v174 offset:28672
	ds_read_b64_tr_b16 v[122:123], v194 offset:28672
	v_exp_f32_e32 v64, v64
	v_exp_f32_e32 v65, v65
	v_exp_f32_e32 v66, v66
	v_exp_f32_e32 v67, v67
	v_pk_add_f32 v[188:189], v[188:189], v[64:65]
	v_pk_add_f32 v[190:191], v[190:191], v[66:67]
	s_waitcnt lgkmcnt(6)
	v_mfma_f32_32x32x16_bf16 v[144:159], v[88:91], v[124:127], v[144:159]
	ds_read_b64_tr_b16 v[124:125], v175 offset:28672
	ds_read_b64_tr_b16 v[126:127], v197 offset:28672
	v_exp_f32_e32 v68, v68
	v_exp_f32_e32 v69, v69
	v_exp_f32_e32 v70, v70
	v_exp_f32_e32 v71, v71
	v_pk_add_f32 v[188:189], v[188:189], v[68:69]
	v_pk_add_f32 v[190:191], v[190:191], v[70:71]
	s_waitcnt lgkmcnt(6)
	v_mfma_f32_32x32x16_bf16 v[198:213], v[92:95], v[112:115], v[198:213]
	v_exp_f32_e32 v72, v72
	v_exp_f32_e32 v73, v73
	v_exp_f32_e32 v74, v74
	v_exp_f32_e32 v75, v75
	v_pk_add_f32 v[188:189], v[188:189], v[72:73]
	v_pk_add_f32 v[190:191], v[190:191], v[74:75]
	s_waitcnt lgkmcnt(4)
	v_mfma_f32_32x32x16_bf16 v[214:229], v[92:95], v[116:119], v[214:229]
	v_exp_f32_e32 v76, v76
	v_exp_f32_e32 v77, v77
	v_exp_f32_e32 v78, v78
	v_exp_f32_e32 v79, v79
	v_pk_add_f32 v[188:189], v[188:189], v[76:77]
	v_pk_add_f32 v[190:191], v[190:191], v[78:79]
	s_waitcnt lgkmcnt(2)
	v_mfma_f32_32x32x16_bf16 v[230:245], v[92:95], v[120:123], v[230:245]
	v_cvt_pk_bf16_f32 v80, v64, v65
	v_cvt_pk_bf16_f32 v81, v66, v67
	v_cvt_pk_bf16_f32 v82, v68, v69
	v_cvt_pk_bf16_f32 v83, v70, v71
	s_waitcnt lgkmcnt(0)
	v_mfma_f32_32x32x16_bf16 v[144:159], v[92:95], v[124:127], v[144:159]
	v_cvt_pk_bf16_f32 v84, v72, v73
	v_cvt_pk_bf16_f32 v85, v74, v75
	v_cvt_pk_bf16_f32 v86, v76, v77
	v_cvt_pk_bf16_f32 v87, v78, v79
.Lpb_h1_2:
	ds_read_b128 v[96:99], v187 offset:40960
	ds_read_b128 v[100:103], v186 offset:40960
	ds_read_b128 v[104:107], v185 offset:40960
	ds_read_b128 v[108:111], v184 offset:40960
	ds_read_b64_tr_b16 v[112:113], v172 offset:32768
	ds_read_b64_tr_b16 v[114:115], v192 offset:32768
	ds_read_b64_tr_b16 v[116:117], v173 offset:32768
	ds_read_b64_tr_b16 v[118:119], v193 offset:32768
	ds_read_b64_tr_b16 v[120:121], v174 offset:32768
	ds_read_b64_tr_b16 v[122:123], v194 offset:32768
	ds_read_b64_tr_b16 v[124:125], v175 offset:32768
	ds_read_b64_tr_b16 v[126:127], v197 offset:32768
	s_waitcnt lgkmcnt(11)
	v_mfma_f32_32x32x16_bf16 v[64:79], v[96:99], v[140:143], 0
	s_waitcnt lgkmcnt(10)
	v_mfma_f32_32x32x16_bf16 v[64:79], v[100:103], v[136:139], v[64:79]
	s_waitcnt lgkmcnt(9)
	v_mfma_f32_32x32x16_bf16 v[64:79], v[104:107], v[132:135], v[64:79]
	s_waitcnt lgkmcnt(8)
	v_mfma_f32_32x32x16_bf16 v[64:79], v[108:111], v[128:131], v[64:79]
	s_waitcnt lgkmcnt(6)
	v_mfma_f32_32x32x16_bf16 v[198:213], v[80:83], v[112:115], v[198:213]
	ds_read_b64_tr_b16 v[112:113], v172 offset:36864
	ds_read_b64_tr_b16 v[114:115], v192 offset:36864
	s_waitcnt lgkmcnt(6)
	v_mfma_f32_32x32x16_bf16 v[214:229], v[80:83], v[116:119], v[214:229]
	ds_read_b64_tr_b16 v[116:117], v173 offset:36864
	ds_read_b64_tr_b16 v[118:119], v193 offset:36864
	s_waitcnt lgkmcnt(6)
	v_mfma_f32_32x32x16_bf16 v[230:245], v[80:83], v[120:123], v[230:245]
	ds_read_b64_tr_b16 v[120:121], v174 offset:36864
	ds_read_b64_tr_b16 v[122:123], v194 offset:36864
	v_exp_f32_e32 v64, v64
	v_exp_f32_e32 v65, v65
	v_exp_f32_e32 v66, v66
	v_exp_f32_e32 v67, v67
	v_pk_add_f32 v[188:189], v[188:189], v[64:65]
	v_pk_add_f32 v[190:191], v[190:191], v[66:67]
	s_waitcnt lgkmcnt(6)
	v_mfma_f32_32x32x16_bf16 v[144:159], v[80:83], v[124:127], v[144:159]
	ds_read_b64_tr_b16 v[124:125], v175 offset:36864
	ds_read_b64_tr_b16 v[126:127], v197 offset:36864
	v_exp_f32_e32 v68, v68
	v_exp_f32_e32 v69, v69
	v_exp_f32_e32 v70, v70
	v_exp_f32_e32 v71, v71
	v_pk_add_f32 v[188:189], v[188:189], v[68:69]
	v_pk_add_f32 v[190:191], v[190:191], v[70:71]
	s_waitcnt lgkmcnt(6)
	v_mfma_f32_32x32x16_bf16 v[198:213], v[84:87], v[112:115], v[198:213]
	v_exp_f32_e32 v72, v72
	v_exp_f32_e32 v73, v73
	v_exp_f32_e32 v74, v74
	v_exp_f32_e32 v75, v75
	v_pk_add_f32 v[188:189], v[188:189], v[72:73]
	v_pk_add_f32 v[190:191], v[190:191], v[74:75]
	s_waitcnt lgkmcnt(4)
	v_mfma_f32_32x32x16_bf16 v[214:229], v[84:87], v[116:119], v[214:229]
	v_exp_f32_e32 v76, v76
	v_exp_f32_e32 v77, v77
	v_exp_f32_e32 v78, v78
	v_exp_f32_e32 v79, v79
	v_pk_add_f32 v[188:189], v[188:189], v[76:77]
	v_pk_add_f32 v[190:191], v[190:191], v[78:79]
	s_waitcnt lgkmcnt(2)
	v_mfma_f32_32x32x16_bf16 v[230:245], v[84:87], v[120:123], v[230:245]
	v_cvt_pk_bf16_f32 v88, v64, v65
	v_cvt_pk_bf16_f32 v89, v66, v67
	v_cvt_pk_bf16_f32 v90, v68, v69
	v_cvt_pk_bf16_f32 v91, v70, v71
	s_waitcnt lgkmcnt(0)
	v_mfma_f32_32x32x16_bf16 v[144:159], v[84:87], v[124:127], v[144:159]
	v_cvt_pk_bf16_f32 v92, v72, v73
	v_cvt_pk_bf16_f32 v93, v74, v75
	v_cvt_pk_bf16_f32 v94, v76, v77
	v_cvt_pk_bf16_f32 v95, v78, v79
	s_cmp_lt_i32 s54, vcc_lo
	s_cbranch_scc1 .Lpb_next_2
	s_nop 1
	ds_read_b64_tr_b16 v[112:113], v172 offset:40960
	ds_read_b64_tr_b16 v[114:115], v192 offset:40960
	ds_read_b64_tr_b16 v[116:117], v173 offset:40960
	ds_read_b64_tr_b16 v[118:119], v193 offset:40960
	ds_read_b64_tr_b16 v[120:121], v174 offset:40960
	ds_read_b64_tr_b16 v[122:123], v194 offset:40960
	ds_read_b64_tr_b16 v[124:125], v175 offset:40960
	ds_read_b64_tr_b16 v[126:127], v197 offset:40960
	s_waitcnt lgkmcnt(6)
	v_mfma_f32_32x32x16_bf16 v[198:213], v[88:91], v[112:115], v[198:213]
	ds_read_b64_tr_b16 v[112:113], v172 offset:45056
	ds_read_b64_tr_b16 v[114:115], v192 offset:45056
	s_waitcnt lgkmcnt(6)
	v_mfma_f32_32x32x16_bf16 v[214:229], v[88:91], v[116:119], v[214:229]
	ds_read_b64_tr_b16 v[116:117], v173 offset:45056
	ds_read_b64_tr_b16 v[118:119], v193 offset:45056
	s_waitcnt lgkmcnt(6)
	v_mfma_f32_32x32x16_bf16 v[230:245], v[88:91], v[120:123], v[230:245]
	ds_read_b64_tr_b16 v[120:121], v174 offset:45056
	ds_read_b64_tr_b16 v[122:123], v194 offset:45056
	s_waitcnt lgkmcnt(6)
	v_mfma_f32_32x32x16_bf16 v[144:159], v[88:91], v[124:127], v[144:159]
	ds_read_b64_tr_b16 v[124:125], v175 offset:45056
	ds_read_b64_tr_b16 v[126:127], v197 offset:45056
	s_waitcnt lgkmcnt(6)
	v_mfma_f32_32x32x16_bf16 v[198:213], v[92:95], v[112:115], v[198:213]
	s_waitcnt lgkmcnt(4)
	v_mfma_f32_32x32x16_bf16 v[214:229], v[92:95], v[116:119], v[214:229]
	s_waitcnt lgkmcnt(2)
	v_mfma_f32_32x32x16_bf16 v[230:245], v[92:95], v[120:123], v[230:245]
	s_waitcnt lgkmcnt(0)
	v_mfma_f32_32x32x16_bf16 v[144:159], v[92:95], v[124:127], v[144:159]

.Lpb_done:
	v_pk_add_f32 v[188:189], v[188:189], v[190:191]
	s_nop 1
	v_add_f32_e32 v188, v188, v189
	ds_bpermute_b32 v190, v169, v188
	s_waitcnt lgkmcnt(0)
	v_add_f32_e32 v188, v188, v190
	v_rcp_f32_e32 v168, v188
	s_nop 0
	v_mul_f32_e32 v168, v181, v168
	v_lshlrev_b32_e32 v64, 4, v183
	v_add_u32_e32 v98, 0, v64
	ds_bpermute_b32 v66, v98, v167
	ds_bpermute_b32 v82, v98, v168
	v_add_u32_e32 v99, 4, v64
	ds_bpermute_b32 v67, v99, v167
	ds_bpermute_b32 v83, v99, v168
	v_add_u32_e32 v100, 8, v64
	ds_bpermute_b32 v68, v100, v167
	ds_bpermute_b32 v84, v100, v168
	v_add_u32_e32 v101, 12, v64
	ds_bpermute_b32 v69, v101, v167
	ds_bpermute_b32 v85, v101, v168
	s_waitcnt lgkmcnt(0)
	v_mul_f32_e32 v198, v198, v82
	v_mul_f32_e32 v214, v214, v82
	v_mul_f32_e32 v230, v230, v82
	v_mul_f32_e32 v144, v144, v82
	v_fma_f32 v0, v0, v66, -v198
	v_fma_f32 v16, v16, v66, -v214
	v_fma_f32 v32, v32, v66, -v230
	v_fma_f32 v48, v48, v66, -v144
	v_mul_f32_e32 v199, v199, v83
	v_mul_f32_e32 v215, v215, v83
	v_mul_f32_e32 v231, v231, v83
	v_mul_f32_e32 v145, v145, v83
	v_fma_f32 v1, v1, v67, -v199
	v_fma_f32 v17, v17, v67, -v215
	v_fma_f32 v33, v33, v67, -v231
	v_fma_f32 v49, v49, v67, -v145
	v_mul_f32_e32 v200, v200, v84
	v_mul_f32_e32 v216, v216, v84
	v_mul_f32_e32 v232, v232, v84
	v_mul_f32_e32 v146, v146, v84
	v_fma_f32 v2, v2, v68, -v200
	v_fma_f32 v18, v18, v68, -v216
	v_fma_f32 v34, v34, v68, -v232
	v_fma_f32 v50, v50, v68, -v146
	v_mul_f32_e32 v201, v201, v85
	v_mul_f32_e32 v217, v217, v85
	v_mul_f32_e32 v233, v233, v85
	v_mul_f32_e32 v147, v147, v85
	v_fma_f32 v3, v3, v69, -v201
	v_fma_f32 v19, v19, v69, -v217
	v_fma_f32 v35, v35, v69, -v233
	v_fma_f32 v51, v51, v69, -v147
	v_add_u32_e32 v98, 32, v64
	ds_bpermute_b32 v70, v98, v167
	ds_bpermute_b32 v86, v98, v168
	v_add_u32_e32 v99, 36, v64
	ds_bpermute_b32 v71, v99, v167
	ds_bpermute_b32 v87, v99, v168
	v_add_u32_e32 v100, 40, v64
	ds_bpermute_b32 v72, v100, v167
	ds_bpermute_b32 v88, v100, v168
	v_add_u32_e32 v101, 44, v64
	ds_bpermute_b32 v73, v101, v167
	ds_bpermute_b32 v89, v101, v168
	s_waitcnt lgkmcnt(0)
	v_mul_f32_e32 v202, v202, v86
	v_mul_f32_e32 v218, v218, v86
	v_mul_f32_e32 v234, v234, v86
	v_mul_f32_e32 v148, v148, v86
	v_fma_f32 v4, v4, v70, -v202
	v_fma_f32 v20, v20, v70, -v218
	v_fma_f32 v36, v36, v70, -v234
	v_fma_f32 v52, v52, v70, -v148
	v_mul_f32_e32 v203, v203, v87
	v_mul_f32_e32 v219, v219, v87
	v_mul_f32_e32 v235, v235, v87
	v_mul_f32_e32 v149, v149, v87
	v_fma_f32 v5, v5, v71, -v203
	v_fma_f32 v21, v21, v71, -v219
	v_fma_f32 v37, v37, v71, -v235
	v_fma_f32 v53, v53, v71, -v149
	v_mul_f32_e32 v204, v204, v88
	v_mul_f32_e32 v220, v220, v88
	v_mul_f32_e32 v236, v236, v88
	v_mul_f32_e32 v150, v150, v88
	v_fma_f32 v6, v6, v72, -v204
	v_fma_f32 v22, v22, v72, -v220
	v_fma_f32 v38, v38, v72, -v236
	v_fma_f32 v54, v54, v72, -v150
	v_mul_f32_e32 v205, v205, v89
	v_mul_f32_e32 v221, v221, v89
	v_mul_f32_e32 v237, v237, v89
	v_mul_f32_e32 v151, v151, v89
	v_fma_f32 v7, v7, v73, -v205
	v_fma_f32 v23, v23, v73, -v221
	v_fma_f32 v39, v39, v73, -v237
	v_fma_f32 v55, v55, v73, -v151
	v_add_u32_e32 v98, 64, v64
	ds_bpermute_b32 v74, v98, v167
	ds_bpermute_b32 v90, v98, v168
	v_add_u32_e32 v99, 68, v64
	ds_bpermute_b32 v75, v99, v167
	ds_bpermute_b32 v91, v99, v168
	v_add_u32_e32 v100, 72, v64
	ds_bpermute_b32 v76, v100, v167
	ds_bpermute_b32 v92, v100, v168
	v_add_u32_e32 v101, 76, v64
	ds_bpermute_b32 v77, v101, v167
	ds_bpermute_b32 v93, v101, v168
	s_waitcnt lgkmcnt(0)
	v_mul_f32_e32 v206, v206, v90
	v_mul_f32_e32 v222, v222, v90
	v_mul_f32_e32 v238, v238, v90
	v_mul_f32_e32 v152, v152, v90
	v_fma_f32 v8, v8, v74, -v206
	v_fma_f32 v24, v24, v74, -v222
	v_fma_f32 v40, v40, v74, -v238
	v_fma_f32 v56, v56, v74, -v152
	v_mul_f32_e32 v207, v207, v91
	v_mul_f32_e32 v223, v223, v91
	v_mul_f32_e32 v239, v239, v91
	v_mul_f32_e32 v153, v153, v91
	v_fma_f32 v9, v9, v75, -v207
	v_fma_f32 v25, v25, v75, -v223
	v_fma_f32 v41, v41, v75, -v239
	v_fma_f32 v57, v57, v75, -v153
	v_mul_f32_e32 v208, v208, v92
	v_mul_f32_e32 v224, v224, v92
	v_mul_f32_e32 v240, v240, v92
	v_mul_f32_e32 v154, v154, v92
	v_fma_f32 v10, v10, v76, -v208
	v_fma_f32 v26, v26, v76, -v224
	v_fma_f32 v42, v42, v76, -v240
	v_fma_f32 v58, v58, v76, -v154
	v_mul_f32_e32 v209, v209, v93
	v_mul_f32_e32 v225, v225, v93
	v_mul_f32_e32 v241, v241, v93
	v_mul_f32_e32 v155, v155, v93
	v_fma_f32 v11, v11, v77, -v209
	v_fma_f32 v27, v27, v77, -v225
	v_fma_f32 v43, v43, v77, -v241
	v_fma_f32 v59, v59, v77, -v155
	v_add_u32_e32 v98, 96, v64
	ds_bpermute_b32 v78, v98, v167
	ds_bpermute_b32 v94, v98, v168
	v_add_u32_e32 v99, 100, v64
	ds_bpermute_b32 v79, v99, v167
	ds_bpermute_b32 v95, v99, v168
	v_add_u32_e32 v100, 104, v64
	ds_bpermute_b32 v80, v100, v167
	ds_bpermute_b32 v96, v100, v168
	v_add_u32_e32 v101, 108, v64
	ds_bpermute_b32 v81, v101, v167
	ds_bpermute_b32 v97, v101, v168
	s_waitcnt lgkmcnt(0)
	v_mul_f32_e32 v210, v210, v94
	v_mul_f32_e32 v226, v226, v94
	v_mul_f32_e32 v242, v242, v94
	v_mul_f32_e32 v156, v156, v94
	v_fma_f32 v12, v12, v78, -v210
	v_fma_f32 v28, v28, v78, -v226
	v_fma_f32 v44, v44, v78, -v242
	v_fma_f32 v60, v60, v78, -v156
	v_mul_f32_e32 v211, v211, v95
	v_mul_f32_e32 v227, v227, v95
	v_mul_f32_e32 v243, v243, v95
	v_mul_f32_e32 v157, v157, v95
	v_fma_f32 v13, v13, v79, -v211
	v_fma_f32 v29, v29, v79, -v227
	v_fma_f32 v45, v45, v79, -v243
	v_fma_f32 v61, v61, v79, -v157
	v_mul_f32_e32 v212, v212, v96
	v_mul_f32_e32 v228, v228, v96
	v_mul_f32_e32 v244, v244, v96
	v_mul_f32_e32 v158, v158, v96
	v_fma_f32 v14, v14, v80, -v212
	v_fma_f32 v30, v30, v80, -v228
	v_fma_f32 v46, v46, v80, -v244
	v_fma_f32 v62, v62, v80, -v158
	v_mul_f32_e32 v213, v213, v97
	v_mul_f32_e32 v229, v229, v97
	v_mul_f32_e32 v245, v245, v97
	v_mul_f32_e32 v159, v159, v97
	v_fma_f32 v15, v15, v81, -v213
	v_fma_f32 v31, v31, v81, -v229
	v_fma_f32 v47, v47, v81, -v245
	v_fma_f32 v63, v63, v81, -v159
	v_and_b32_e32 v65, 31, v165
	v_lshlrev_b32_e32 v64, 2, v65
	global_load_dword v100, v64, s[44:45]
	global_load_dword v101, v64, s[44:45] offset:128
	global_load_dword v102, v64, s[44:45] offset:256
	global_load_dword v103, v64, s[44:45] offset:384
	v_mul_f32_e32 v66, v0, v0
	v_fmac_f32_e32 v66, v16, v16
	v_fmac_f32_e32 v66, v32, v32
	v_fmac_f32_e32 v66, v48, v48
	v_mul_f32_e32 v67, v1, v1
	v_fmac_f32_e32 v67, v17, v17
	v_fmac_f32_e32 v67, v33, v33
	v_fmac_f32_e32 v67, v49, v49
	v_mul_f32_e32 v68, v2, v2
	v_fmac_f32_e32 v68, v18, v18
	v_fmac_f32_e32 v68, v34, v34
	v_fmac_f32_e32 v68, v50, v50
	v_mul_f32_e32 v69, v3, v3
	v_fmac_f32_e32 v69, v19, v19
	v_fmac_f32_e32 v69, v35, v35
	v_fmac_f32_e32 v69, v51, v51
	v_mul_f32_e32 v70, v4, v4
	v_fmac_f32_e32 v70, v20, v20
	v_fmac_f32_e32 v70, v36, v36
	v_fmac_f32_e32 v70, v52, v52
	v_mul_f32_e32 v71, v5, v5
	v_fmac_f32_e32 v71, v21, v21
	v_fmac_f32_e32 v71, v37, v37
	v_fmac_f32_e32 v71, v53, v53
	v_mul_f32_e32 v72, v6, v6
	v_fmac_f32_e32 v72, v22, v22
	v_fmac_f32_e32 v72, v38, v38
	v_fmac_f32_e32 v72, v54, v54
	v_mul_f32_e32 v73, v7, v7
	v_fmac_f32_e32 v73, v23, v23
	v_fmac_f32_e32 v73, v39, v39
	v_fmac_f32_e32 v73, v55, v55
	v_mul_f32_e32 v74, v8, v8
	v_fmac_f32_e32 v74, v24, v24
	v_fmac_f32_e32 v74, v40, v40
	v_fmac_f32_e32 v74, v56, v56
	v_mul_f32_e32 v75, v9, v9
	v_fmac_f32_e32 v75, v25, v25
	v_fmac_f32_e32 v75, v41, v41
	v_fmac_f32_e32 v75, v57, v57
	v_mul_f32_e32 v76, v10, v10
	v_fmac_f32_e32 v76, v26, v26
	v_fmac_f32_e32 v76, v42, v42
	v_fmac_f32_e32 v76, v58, v58
	v_mul_f32_e32 v77, v11, v11
	v_fmac_f32_e32 v77, v27, v27
	v_fmac_f32_e32 v77, v43, v43
	v_fmac_f32_e32 v77, v59, v59
	v_mul_f32_e32 v78, v12, v12
	v_fmac_f32_e32 v78, v28, v28
	v_fmac_f32_e32 v78, v44, v44
	v_fmac_f32_e32 v78, v60, v60
	v_mul_f32_e32 v79, v13, v13
	v_fmac_f32_e32 v79, v29, v29
	v_fmac_f32_e32 v79, v45, v45
	v_fmac_f32_e32 v79, v61, v61
	v_mul_f32_e32 v80, v14, v14
	v_fmac_f32_e32 v80, v30, v30
	v_fmac_f32_e32 v80, v46, v46
	v_fmac_f32_e32 v80, v62, v62
	v_mul_f32_e32 v81, v15, v15
	v_fmac_f32_e32 v81, v31, v31
	v_fmac_f32_e32 v81, v47, v47
	v_fmac_f32_e32 v81, v63, v63
	ds_bpermute_b32 v82, v177, v66
	ds_bpermute_b32 v83, v177, v67
	ds_bpermute_b32 v84, v177, v68
	ds_bpermute_b32 v85, v177, v69
	ds_bpermute_b32 v86, v177, v70
	ds_bpermute_b32 v87, v177, v71
	ds_bpermute_b32 v88, v177, v72
	ds_bpermute_b32 v89, v177, v73
	s_waitcnt lgkmcnt(7)
	v_add_f32_e32 v66, v66, v82
	s_waitcnt lgkmcnt(6)
	v_add_f32_e32 v67, v67, v83
	s_waitcnt lgkmcnt(5)
	v_add_f32_e32 v68, v68, v84
	s_waitcnt lgkmcnt(4)
	v_add_f32_e32 v69, v69, v85
	s_waitcnt lgkmcnt(3)
	v_add_f32_e32 v70, v70, v86
	s_waitcnt lgkmcnt(2)
	v_add_f32_e32 v71, v71, v87
	s_waitcnt lgkmcnt(1)
	v_add_f32_e32 v72, v72, v88
	s_waitcnt lgkmcnt(0)
	v_add_f32_e32 v73, v73, v89
	ds_bpermute_b32 v90, v177, v74
	ds_bpermute_b32 v91, v177, v75
	ds_bpermute_b32 v92, v177, v76
	ds_bpermute_b32 v93, v177, v77
	ds_bpermute_b32 v94, v177, v78
	ds_bpermute_b32 v95, v177, v79
	ds_bpermute_b32 v96, v177, v80
	ds_bpermute_b32 v97, v177, v81
	s_waitcnt lgkmcnt(7)
	v_add_f32_e32 v74, v74, v90
	s_waitcnt lgkmcnt(6)
	v_add_f32_e32 v75, v75, v91
	s_waitcnt lgkmcnt(5)
	v_add_f32_e32 v76, v76, v92
	s_waitcnt lgkmcnt(4)
	v_add_f32_e32 v77, v77, v93
	s_waitcnt lgkmcnt(3)
	v_add_f32_e32 v78, v78, v94
	s_waitcnt lgkmcnt(2)
	v_add_f32_e32 v79, v79, v95
	s_waitcnt lgkmcnt(1)
	v_add_f32_e32 v80, v80, v96
	s_waitcnt lgkmcnt(0)
	v_add_f32_e32 v81, v81, v97
	ds_bpermute_b32 v82, v178, v66
	ds_bpermute_b32 v83, v178, v67
	ds_bpermute_b32 v84, v178, v68
	ds_bpermute_b32 v85, v178, v69
	ds_bpermute_b32 v86, v178, v70
	ds_bpermute_b32 v87, v178, v71
	ds_bpermute_b32 v88, v178, v72
	ds_bpermute_b32 v89, v178, v73
	s_waitcnt lgkmcnt(7)
	v_add_f32_e32 v66, v66, v82
	s_waitcnt lgkmcnt(6)
	v_add_f32_e32 v67, v67, v83
	s_waitcnt lgkmcnt(5)
	v_add_f32_e32 v68, v68, v84
	s_waitcnt lgkmcnt(4)
	v_add_f32_e32 v69, v69, v85
	s_waitcnt lgkmcnt(3)
	v_add_f32_e32 v70, v70, v86
	s_waitcnt lgkmcnt(2)
	v_add_f32_e32 v71, v71, v87
	s_waitcnt lgkmcnt(1)
	v_add_f32_e32 v72, v72, v88
	s_waitcnt lgkmcnt(0)
	v_add_f32_e32 v73, v73, v89
	ds_bpermute_b32 v90, v178, v74
	ds_bpermute_b32 v91, v178, v75
	ds_bpermute_b32 v92, v178, v76
	ds_bpermute_b32 v93, v178, v77
	ds_bpermute_b32 v94, v178, v78
	ds_bpermute_b32 v95, v178, v79
	ds_bpermute_b32 v96, v178, v80
	ds_bpermute_b32 v97, v178, v81
	s_waitcnt lgkmcnt(7)
	v_add_f32_e32 v74, v74, v90
	s_waitcnt lgkmcnt(6)
	v_add_f32_e32 v75, v75, v91
	s_waitcnt lgkmcnt(5)
	v_add_f32_e32 v76, v76, v92
	s_waitcnt lgkmcnt(4)
	v_add_f32_e32 v77, v77, v93
	s_waitcnt lgkmcnt(3)
	v_add_f32_e32 v78, v78, v94
	s_waitcnt lgkmcnt(2)
	v_add_f32_e32 v79, v79, v95
	s_waitcnt lgkmcnt(1)
	v_add_f32_e32 v80, v80, v96
	s_waitcnt lgkmcnt(0)
	v_add_f32_e32 v81, v81, v97
	ds_bpermute_b32 v82, v179, v66
	ds_bpermute_b32 v83, v179, v67
	ds_bpermute_b32 v84, v179, v68
	ds_bpermute_b32 v85, v179, v69
	ds_bpermute_b32 v86, v179, v70
	ds_bpermute_b32 v87, v179, v71
	ds_bpermute_b32 v88, v179, v72
	ds_bpermute_b32 v89, v179, v73
	s_waitcnt lgkmcnt(7)
	v_add_f32_e32 v66, v66, v82
	s_waitcnt lgkmcnt(6)
	v_add_f32_e32 v67, v67, v83
	s_waitcnt lgkmcnt(5)
	v_add_f32_e32 v68, v68, v84
	s_waitcnt lgkmcnt(4)
	v_add_f32_e32 v69, v69, v85
	s_waitcnt lgkmcnt(3)
	v_add_f32_e32 v70, v70, v86
	s_waitcnt lgkmcnt(2)
	v_add_f32_e32 v71, v71, v87
	s_waitcnt lgkmcnt(1)
	v_add_f32_e32 v72, v72, v88
	s_waitcnt lgkmcnt(0)
	v_add_f32_e32 v73, v73, v89
	ds_bpermute_b32 v90, v179, v74
	ds_bpermute_b32 v91, v179, v75
	ds_bpermute_b32 v92, v179, v76
	ds_bpermute_b32 v93, v179, v77
	ds_bpermute_b32 v94, v179, v78
	ds_bpermute_b32 v95, v179, v79
	ds_bpermute_b32 v96, v179, v80
	ds_bpermute_b32 v97, v179, v81
	s_waitcnt lgkmcnt(7)
	v_add_f32_e32 v74, v74, v90
	s_waitcnt lgkmcnt(6)
	v_add_f32_e32 v75, v75, v91
	s_waitcnt lgkmcnt(5)
	v_add_f32_e32 v76, v76, v92
	s_waitcnt lgkmcnt(4)
	v_add_f32_e32 v77, v77, v93
	s_waitcnt lgkmcnt(3)
	v_add_f32_e32 v78, v78, v94
	s_waitcnt lgkmcnt(2)
	v_add_f32_e32 v79, v79, v95
	s_waitcnt lgkmcnt(1)
	v_add_f32_e32 v80, v80, v96
	s_waitcnt lgkmcnt(0)
	v_add_f32_e32 v81, v81, v97
	ds_bpermute_b32 v82, v180, v66
	ds_bpermute_b32 v83, v180, v67
	ds_bpermute_b32 v84, v180, v68
	ds_bpermute_b32 v85, v180, v69
	ds_bpermute_b32 v86, v180, v70
	ds_bpermute_b32 v87, v180, v71
	ds_bpermute_b32 v88, v180, v72
	ds_bpermute_b32 v89, v180, v73
	s_waitcnt lgkmcnt(7)
	v_add_f32_e32 v66, v66, v82
	s_waitcnt lgkmcnt(6)
	v_add_f32_e32 v67, v67, v83
	s_waitcnt lgkmcnt(5)
	v_add_f32_e32 v68, v68, v84
	s_waitcnt lgkmcnt(4)
	v_add_f32_e32 v69, v69, v85
	s_waitcnt lgkmcnt(3)
	v_add_f32_e32 v70, v70, v86
	s_waitcnt lgkmcnt(2)
	v_add_f32_e32 v71, v71, v87
	s_waitcnt lgkmcnt(1)
	v_add_f32_e32 v72, v72, v88
	s_waitcnt lgkmcnt(0)
	v_add_f32_e32 v73, v73, v89
	ds_bpermute_b32 v90, v180, v74
	ds_bpermute_b32 v91, v180, v75
	ds_bpermute_b32 v92, v180, v76
	ds_bpermute_b32 v93, v180, v77
	ds_bpermute_b32 v94, v180, v78
	ds_bpermute_b32 v95, v180, v79
	ds_bpermute_b32 v96, v180, v80
	ds_bpermute_b32 v97, v180, v81
	s_waitcnt lgkmcnt(7)
	v_add_f32_e32 v74, v74, v90
	s_waitcnt lgkmcnt(6)
	v_add_f32_e32 v75, v75, v91
	s_waitcnt lgkmcnt(5)
	v_add_f32_e32 v76, v76, v92
	s_waitcnt lgkmcnt(4)
	v_add_f32_e32 v77, v77, v93
	s_waitcnt lgkmcnt(3)
	v_add_f32_e32 v78, v78, v94
	s_waitcnt lgkmcnt(2)
	v_add_f32_e32 v79, v79, v95
	s_waitcnt lgkmcnt(1)
	v_add_f32_e32 v80, v80, v96
	s_waitcnt lgkmcnt(0)
	v_add_f32_e32 v81, v81, v97
	ds_bpermute_b32 v82, v163, v66
	ds_bpermute_b32 v83, v163, v67
	ds_bpermute_b32 v84, v163, v68
	ds_bpermute_b32 v85, v163, v69
	ds_bpermute_b32 v86, v163, v70
	ds_bpermute_b32 v87, v163, v71
	ds_bpermute_b32 v88, v163, v72
	ds_bpermute_b32 v89, v163, v73
	s_waitcnt lgkmcnt(7)
	v_add_f32_e32 v66, v66, v82
	s_waitcnt lgkmcnt(6)
	v_add_f32_e32 v67, v67, v83
	s_waitcnt lgkmcnt(5)
	v_add_f32_e32 v68, v68, v84
	s_waitcnt lgkmcnt(4)
	v_add_f32_e32 v69, v69, v85
	s_waitcnt lgkmcnt(3)
	v_add_f32_e32 v70, v70, v86
	s_waitcnt lgkmcnt(2)
	v_add_f32_e32 v71, v71, v87
	s_waitcnt lgkmcnt(1)
	v_add_f32_e32 v72, v72, v88
	s_waitcnt lgkmcnt(0)
	v_add_f32_e32 v73, v73, v89
	ds_bpermute_b32 v90, v163, v74
	ds_bpermute_b32 v91, v163, v75
	ds_bpermute_b32 v92, v163, v76
	ds_bpermute_b32 v93, v163, v77
	ds_bpermute_b32 v94, v163, v78
	ds_bpermute_b32 v95, v163, v79
	ds_bpermute_b32 v96, v163, v80
	ds_bpermute_b32 v97, v163, v81
	s_waitcnt lgkmcnt(7)
	v_add_f32_e32 v74, v74, v90
	s_waitcnt lgkmcnt(6)
	v_add_f32_e32 v75, v75, v91
	s_waitcnt lgkmcnt(5)
	v_add_f32_e32 v76, v76, v92
	s_waitcnt lgkmcnt(4)
	v_add_f32_e32 v77, v77, v93
	s_waitcnt lgkmcnt(3)
	v_add_f32_e32 v78, v78, v94
	s_waitcnt lgkmcnt(2)
	v_add_f32_e32 v79, v79, v95
	s_waitcnt lgkmcnt(1)
	v_add_f32_e32 v80, v80, v96
	s_waitcnt lgkmcnt(0)
	v_add_f32_e32 v81, v81, v97
	v_fmamk_f32 v66, v66, 0x3c000000, v182
	v_fmamk_f32 v67, v67, 0x3c000000, v182
	v_fmamk_f32 v68, v68, 0x3c000000, v182
	v_fmamk_f32 v69, v69, 0x3c000000, v182
	v_fmamk_f32 v70, v70, 0x3c000000, v182
	v_fmamk_f32 v71, v71, 0x3c000000, v182
	v_fmamk_f32 v72, v72, 0x3c000000, v182
	v_fmamk_f32 v73, v73, 0x3c000000, v182
	v_fmamk_f32 v74, v74, 0x3c000000, v182
	v_fmamk_f32 v75, v75, 0x3c000000, v182
	v_fmamk_f32 v76, v76, 0x3c000000, v182
	v_fmamk_f32 v77, v77, 0x3c000000, v182
	v_fmamk_f32 v78, v78, 0x3c000000, v182
	v_fmamk_f32 v79, v79, 0x3c000000, v182
	v_fmamk_f32 v80, v80, 0x3c000000, v182
	v_fmamk_f32 v81, v81, 0x3c000000, v182
	v_rsq_f32_e32 v66, v66
	v_rsq_f32_e32 v67, v67
	v_rsq_f32_e32 v68, v68
	v_rsq_f32_e32 v69, v69
	v_rsq_f32_e32 v70, v70
	v_rsq_f32_e32 v71, v71
	v_rsq_f32_e32 v72, v72
	v_rsq_f32_e32 v73, v73
	v_rsq_f32_e32 v74, v74
	v_rsq_f32_e32 v75, v75
	v_rsq_f32_e32 v76, v76
	v_rsq_f32_e32 v77, v77
	v_rsq_f32_e32 v78, v78
	v_rsq_f32_e32 v79, v79
	v_rsq_f32_e32 v80, v80
	v_rsq_f32_e32 v81, v81
	s_waitcnt vmcnt(0)
	v_mul_f32_e32 v100, 0x3f4ccccd, v100
	v_mul_f32_e32 v101, 0x3f4ccccd, v101
	v_mul_f32_e32 v102, 0x3f4ccccd, v102
	v_mul_f32_e32 v103, 0x3f4ccccd, v103
	s_lshl_b32 s60, s14, 11
	s_lshl_b32 s61, s12, 1
	s_add_i32 s60, s60, s61
	v_lshlrev_b32_e32 v64, 1, v65
	v_lshl_add_u32 v64, v183, 13, v64
	v_add_u32_e32 v64, s60, v64
	s_mov_b32 s60, s3
	s_mov_b32 s61, s30
	v_mul_f32_e32 v0, v0, v66
	v_mul_f32_e32 v16, v16, v66
	v_mul_f32_e32 v32, v32, v66
	v_mul_f32_e32 v48, v48, v66
	v_mul_f32_e32 v0, v100, v0
	v_mul_f32_e32 v16, v101, v16
	v_mul_f32_e32 v32, v102, v32
	v_mul_f32_e32 v48, v103, v48
	v_cvt_pk_bf16_f32 v0, v0, v0
	v_cvt_pk_bf16_f32 v16, v16, v16
	v_cvt_pk_bf16_f32 v32, v32, v32
	v_cvt_pk_bf16_f32 v48, v48, v48
	global_store_short v64, v0, s[60:61]
	global_store_short v64, v16, s[60:61] offset:64
	global_store_short v64, v32, s[60:61] offset:128
	global_store_short v64, v48, s[60:61] offset:192
	v_add_u32_e32 v65, 0x800, v64
	v_mul_f32_e32 v1, v1, v67
	v_mul_f32_e32 v17, v17, v67
	v_mul_f32_e32 v33, v33, v67
	v_mul_f32_e32 v49, v49, v67
	v_mul_f32_e32 v1, v100, v1
	v_mul_f32_e32 v17, v101, v17
	v_mul_f32_e32 v33, v102, v33
	v_mul_f32_e32 v49, v103, v49
	v_cvt_pk_bf16_f32 v1, v1, v1
	v_cvt_pk_bf16_f32 v17, v17, v17
	v_cvt_pk_bf16_f32 v33, v33, v33
	v_cvt_pk_bf16_f32 v49, v49, v49
	global_store_short v65, v1, s[60:61]
	global_store_short v65, v17, s[60:61] offset:64
	global_store_short v65, v33, s[60:61] offset:128
	global_store_short v65, v49, s[60:61] offset:192
	v_add_u32_e32 v65, 0x1000, v64
	v_mul_f32_e32 v2, v2, v68
	v_mul_f32_e32 v18, v18, v68
	v_mul_f32_e32 v34, v34, v68
	v_mul_f32_e32 v50, v50, v68
	v_mul_f32_e32 v2, v100, v2
	v_mul_f32_e32 v18, v101, v18
	v_mul_f32_e32 v34, v102, v34
	v_mul_f32_e32 v50, v103, v50
	v_cvt_pk_bf16_f32 v2, v2, v2
	v_cvt_pk_bf16_f32 v18, v18, v18
	v_cvt_pk_bf16_f32 v34, v34, v34
	v_cvt_pk_bf16_f32 v50, v50, v50
	global_store_short v65, v2, s[60:61]
	global_store_short v65, v18, s[60:61] offset:64
	global_store_short v65, v34, s[60:61] offset:128
	global_store_short v65, v50, s[60:61] offset:192
	v_add_u32_e32 v65, 0x1800, v64
	v_mul_f32_e32 v3, v3, v69
	v_mul_f32_e32 v19, v19, v69
	v_mul_f32_e32 v35, v35, v69
	v_mul_f32_e32 v51, v51, v69
	v_mul_f32_e32 v3, v100, v3
	v_mul_f32_e32 v19, v101, v19
	v_mul_f32_e32 v35, v102, v35
	v_mul_f32_e32 v51, v103, v51
	v_cvt_pk_bf16_f32 v3, v3, v3
	v_cvt_pk_bf16_f32 v19, v19, v19
	v_cvt_pk_bf16_f32 v35, v35, v35
	v_cvt_pk_bf16_f32 v51, v51, v51
	global_store_short v65, v3, s[60:61]
	global_store_short v65, v19, s[60:61] offset:64
	global_store_short v65, v35, s[60:61] offset:128
	global_store_short v65, v51, s[60:61] offset:192
	v_add_u32_e32 v65, 0x4000, v64
	v_mul_f32_e32 v4, v4, v70
	v_mul_f32_e32 v20, v20, v70
	v_mul_f32_e32 v36, v36, v70
	v_mul_f32_e32 v52, v52, v70
	v_mul_f32_e32 v4, v100, v4
	v_mul_f32_e32 v20, v101, v20
	v_mul_f32_e32 v36, v102, v36
	v_mul_f32_e32 v52, v103, v52
	v_cvt_pk_bf16_f32 v4, v4, v4
	v_cvt_pk_bf16_f32 v20, v20, v20
	v_cvt_pk_bf16_f32 v36, v36, v36
	v_cvt_pk_bf16_f32 v52, v52, v52
	global_store_short v65, v4, s[60:61]
	global_store_short v65, v20, s[60:61] offset:64
	global_store_short v65, v36, s[60:61] offset:128
	global_store_short v65, v52, s[60:61] offset:192
	v_add_u32_e32 v65, 0x4800, v64
	v_mul_f32_e32 v5, v5, v71
	v_mul_f32_e32 v21, v21, v71
	v_mul_f32_e32 v37, v37, v71
	v_mul_f32_e32 v53, v53, v71
	v_mul_f32_e32 v5, v100, v5
	v_mul_f32_e32 v21, v101, v21
	v_mul_f32_e32 v37, v102, v37
	v_mul_f32_e32 v53, v103, v53
	v_cvt_pk_bf16_f32 v5, v5, v5
	v_cvt_pk_bf16_f32 v21, v21, v21
	v_cvt_pk_bf16_f32 v37, v37, v37
	v_cvt_pk_bf16_f32 v53, v53, v53
	global_store_short v65, v5, s[60:61]
	global_store_short v65, v21, s[60:61] offset:64
	global_store_short v65, v37, s[60:61] offset:128
	global_store_short v65, v53, s[60:61] offset:192
	v_add_u32_e32 v65, 0x5000, v64
	v_mul_f32_e32 v6, v6, v72
	v_mul_f32_e32 v22, v22, v72
	v_mul_f32_e32 v38, v38, v72
	v_mul_f32_e32 v54, v54, v72
	v_mul_f32_e32 v6, v100, v6
	v_mul_f32_e32 v22, v101, v22
	v_mul_f32_e32 v38, v102, v38
	v_mul_f32_e32 v54, v103, v54
	v_cvt_pk_bf16_f32 v6, v6, v6
	v_cvt_pk_bf16_f32 v22, v22, v22
	v_cvt_pk_bf16_f32 v38, v38, v38
	v_cvt_pk_bf16_f32 v54, v54, v54
	global_store_short v65, v6, s[60:61]
	global_store_short v65, v22, s[60:61] offset:64
	global_store_short v65, v38, s[60:61] offset:128
	global_store_short v65, v54, s[60:61] offset:192
	v_add_u32_e32 v65, 0x5800, v64
	v_mul_f32_e32 v7, v7, v73
	v_mul_f32_e32 v23, v23, v73
	v_mul_f32_e32 v39, v39, v73
	v_mul_f32_e32 v55, v55, v73
	v_mul_f32_e32 v7, v100, v7
	v_mul_f32_e32 v23, v101, v23
	v_mul_f32_e32 v39, v102, v39
	v_mul_f32_e32 v55, v103, v55
	v_cvt_pk_bf16_f32 v7, v7, v7
	v_cvt_pk_bf16_f32 v23, v23, v23
	v_cvt_pk_bf16_f32 v39, v39, v39
	v_cvt_pk_bf16_f32 v55, v55, v55
	global_store_short v65, v7, s[60:61]
	global_store_short v65, v23, s[60:61] offset:64
	global_store_short v65, v39, s[60:61] offset:128
	global_store_short v65, v55, s[60:61] offset:192
	v_add_u32_e32 v65, 0x8000, v64
	v_mul_f32_e32 v8, v8, v74
	v_mul_f32_e32 v24, v24, v74
	v_mul_f32_e32 v40, v40, v74
	v_mul_f32_e32 v56, v56, v74
	v_mul_f32_e32 v8, v100, v8
	v_mul_f32_e32 v24, v101, v24
	v_mul_f32_e32 v40, v102, v40
	v_mul_f32_e32 v56, v103, v56
	v_cvt_pk_bf16_f32 v8, v8, v8
	v_cvt_pk_bf16_f32 v24, v24, v24
	v_cvt_pk_bf16_f32 v40, v40, v40
	v_cvt_pk_bf16_f32 v56, v56, v56
	global_store_short v65, v8, s[60:61]
	global_store_short v65, v24, s[60:61] offset:64
	global_store_short v65, v40, s[60:61] offset:128
	global_store_short v65, v56, s[60:61] offset:192
	v_add_u32_e32 v65, 0x8800, v64
	v_mul_f32_e32 v9, v9, v75
	v_mul_f32_e32 v25, v25, v75
	v_mul_f32_e32 v41, v41, v75
	v_mul_f32_e32 v57, v57, v75
	v_mul_f32_e32 v9, v100, v9
	v_mul_f32_e32 v25, v101, v25
	v_mul_f32_e32 v41, v102, v41
	v_mul_f32_e32 v57, v103, v57
	v_cvt_pk_bf16_f32 v9, v9, v9
	v_cvt_pk_bf16_f32 v25, v25, v25
	v_cvt_pk_bf16_f32 v41, v41, v41
	v_cvt_pk_bf16_f32 v57, v57, v57
	global_store_short v65, v9, s[60:61]
	global_store_short v65, v25, s[60:61] offset:64
	global_store_short v65, v41, s[60:61] offset:128
	global_store_short v65, v57, s[60:61] offset:192
	v_add_u32_e32 v65, 0x9000, v64
	v_mul_f32_e32 v10, v10, v76
	v_mul_f32_e32 v26, v26, v76
	v_mul_f32_e32 v42, v42, v76
	v_mul_f32_e32 v58, v58, v76
	v_mul_f32_e32 v10, v100, v10
	v_mul_f32_e32 v26, v101, v26
	v_mul_f32_e32 v42, v102, v42
	v_mul_f32_e32 v58, v103, v58
	v_cvt_pk_bf16_f32 v10, v10, v10
	v_cvt_pk_bf16_f32 v26, v26, v26
	v_cvt_pk_bf16_f32 v42, v42, v42
	v_cvt_pk_bf16_f32 v58, v58, v58
	global_store_short v65, v10, s[60:61]
	global_store_short v65, v26, s[60:61] offset:64
	global_store_short v65, v42, s[60:61] offset:128
	global_store_short v65, v58, s[60:61] offset:192
	v_add_u32_e32 v65, 0x9800, v64
	v_mul_f32_e32 v11, v11, v77
	v_mul_f32_e32 v27, v27, v77
	v_mul_f32_e32 v43, v43, v77
	v_mul_f32_e32 v59, v59, v77
	v_mul_f32_e32 v11, v100, v11
	v_mul_f32_e32 v27, v101, v27
	v_mul_f32_e32 v43, v102, v43
	v_mul_f32_e32 v59, v103, v59
	v_cvt_pk_bf16_f32 v11, v11, v11
	v_cvt_pk_bf16_f32 v27, v27, v27
	v_cvt_pk_bf16_f32 v43, v43, v43
	v_cvt_pk_bf16_f32 v59, v59, v59
	global_store_short v65, v11, s[60:61]
	global_store_short v65, v27, s[60:61] offset:64
	global_store_short v65, v43, s[60:61] offset:128
	global_store_short v65, v59, s[60:61] offset:192
	v_add_u32_e32 v65, 0xc000, v64
	v_mul_f32_e32 v12, v12, v78
	v_mul_f32_e32 v28, v28, v78
	v_mul_f32_e32 v44, v44, v78
	v_mul_f32_e32 v60, v60, v78
	v_mul_f32_e32 v12, v100, v12
	v_mul_f32_e32 v28, v101, v28
	v_mul_f32_e32 v44, v102, v44
	v_mul_f32_e32 v60, v103, v60
	v_cvt_pk_bf16_f32 v12, v12, v12
	v_cvt_pk_bf16_f32 v28, v28, v28
	v_cvt_pk_bf16_f32 v44, v44, v44
	v_cvt_pk_bf16_f32 v60, v60, v60
	global_store_short v65, v12, s[60:61]
	global_store_short v65, v28, s[60:61] offset:64
	global_store_short v65, v44, s[60:61] offset:128
	global_store_short v65, v60, s[60:61] offset:192
	v_add_u32_e32 v65, 0xc800, v64
	v_mul_f32_e32 v13, v13, v79
	v_mul_f32_e32 v29, v29, v79
	v_mul_f32_e32 v45, v45, v79
	v_mul_f32_e32 v61, v61, v79
	v_mul_f32_e32 v13, v100, v13
	v_mul_f32_e32 v29, v101, v29
	v_mul_f32_e32 v45, v102, v45
	v_mul_f32_e32 v61, v103, v61
	v_cvt_pk_bf16_f32 v13, v13, v13
	v_cvt_pk_bf16_f32 v29, v29, v29
	v_cvt_pk_bf16_f32 v45, v45, v45
	v_cvt_pk_bf16_f32 v61, v61, v61
	global_store_short v65, v13, s[60:61]
	global_store_short v65, v29, s[60:61] offset:64
	global_store_short v65, v45, s[60:61] offset:128
	global_store_short v65, v61, s[60:61] offset:192
	v_add_u32_e32 v65, 0xd000, v64
	v_mul_f32_e32 v14, v14, v80
	v_mul_f32_e32 v30, v30, v80
	v_mul_f32_e32 v46, v46, v80
	v_mul_f32_e32 v62, v62, v80
	v_mul_f32_e32 v14, v100, v14
	v_mul_f32_e32 v30, v101, v30
	v_mul_f32_e32 v46, v102, v46
	v_mul_f32_e32 v62, v103, v62
	v_cvt_pk_bf16_f32 v14, v14, v14
	v_cvt_pk_bf16_f32 v30, v30, v30
	v_cvt_pk_bf16_f32 v46, v46, v46
	v_cvt_pk_bf16_f32 v62, v62, v62
	global_store_short v65, v14, s[60:61]
	global_store_short v65, v30, s[60:61] offset:64
	global_store_short v65, v46, s[60:61] offset:128
	global_store_short v65, v62, s[60:61] offset:192
	v_add_u32_e32 v65, 0xd800, v64
	v_mul_f32_e32 v15, v15, v81
	v_mul_f32_e32 v31, v31, v81
	v_mul_f32_e32 v47, v47, v81
	v_mul_f32_e32 v63, v63, v81
	v_mul_f32_e32 v15, v100, v15
	v_mul_f32_e32 v31, v101, v31
	v_mul_f32_e32 v47, v102, v47
	v_mul_f32_e32 v63, v103, v63
	v_cvt_pk_bf16_f32 v15, v15, v15
	v_cvt_pk_bf16_f32 v31, v31, v31
	v_cvt_pk_bf16_f32 v47, v47, v47
	v_cvt_pk_bf16_f32 v63, v63, v63
	global_store_short v65, v15, s[60:61]
	global_store_short v65, v31, s[60:61] offset:64
	global_store_short v65, v47, s[60:61] offset:128
	global_store_short v65, v63, s[60:61] offset:192
	v_mov_b32_e32 v242, v246
	v_mov_b32_e32 v243, v247
	v_mov_b32_e32 v167, 0
	s_mov_b32 m0, vcc_hi
	s_add_i32 s77, s77, s74
	s_cmpk_lt_i32 s77, 0x200
	s_waitcnt vmcnt(0) lgkmcnt(0)
	s_barrier
	s_cbranch_scc1 .LBB0_209
